# GEMM K-loop back-edge rotation (loop-carried SALU moved ahead of the loop-back barrier) in all 9 GEMM loops
# baseline (speedup 1.0000x reference)
.Lrot9_body:
	ds_read_b128 v[144:147], v156
	ds_read_b128 v[148:151], v156 offset:1024
	ds_read_b128 v[152:155], v156 offset:2048
	ds_read_b128 v[160:163], v156 offset:3072
	v_add_u32_e32 v156, s63, v141
	ds_read_b128 v[164:167], v156
	ds_read_b128 v[168:171], v156 offset:1024
	ds_read_b128 v[172:175], v156 offset:2048
	ds_read_b128 v[176:179], v156 offset:3072
	v_lshl_add_u64 v[156:157], s[28:29], 0, v[136:137]
	s_add_i32 m0, s47, 0xc000
	ds_read_b128 v[180:183], v143
	ds_read_b128 v[184:187], v143 offset:1024
	ds_read_b128 v[188:191], v143 offset:2048
	ds_read_b128 v[192:195], v143 offset:3072
	ds_read_b128 v[214:217], v143 offset:4096
	ds_read_b128 v[218:221], v143 offset:5120
	ds_read_b128 v[222:225], v143 offset:6144
	ds_read_b128 v[226:229], v143 offset:7168
	global_load_lds_dwordx4 v[156:157], off
	v_lshl_add_u64 v[156:157], s[28:29], 0, v[138:139]
	s_add_i32 m0, s47, 0xe000
	s_nop 0
	global_load_lds_dwordx4 v[156:157], off
	s_waitcnt vmcnt(8)
	s_waitcnt lgkmcnt(0)
	s_barrier
	s_setprio 1
	s_waitcnt lgkmcnt(0)
	v_mfma_f32_16x16x32_bf16 v[122:125], v[144:147], v[180:183], v[122:125]
	v_mfma_f32_16x16x32_bf16 v[118:121], v[152:155], v[180:183], v[118:121]
	v_mfma_f32_16x16x32_bf16 v[110:113], v[144:147], v[188:191], v[110:113]
	v_mfma_f32_16x16x32_bf16 v[102:105], v[152:155], v[188:191], v[102:105]
	v_mfma_f32_16x16x32_bf16 v[94:97], v[144:147], v[214:217], v[94:97]
	v_mfma_f32_16x16x32_bf16 v[84:87], v[152:155], v[214:217], v[84:87]
	v_mfma_f32_16x16x32_bf16 v[76:79], v[144:147], v[222:225], v[76:79]
	v_mfma_f32_16x16x32_bf16 v[68:71], v[152:155], v[222:225], v[68:71]
	v_mfma_f32_16x16x32_bf16 v[122:125], v[148:151], v[184:187], v[122:125]
	v_mfma_f32_16x16x32_bf16 v[118:121], v[160:163], v[184:187], v[118:121]
	v_mfma_f32_16x16x32_bf16 v[110:113], v[148:151], v[192:195], v[110:113]
	v_mfma_f32_16x16x32_bf16 v[102:105], v[160:163], v[192:195], v[102:105]
	v_mfma_f32_16x16x32_bf16 v[94:97], v[148:151], v[218:221], v[94:97]
	v_mfma_f32_16x16x32_bf16 v[84:87], v[160:163], v[218:221], v[84:87]
	v_mfma_f32_16x16x32_bf16 v[76:79], v[148:151], v[226:229], v[76:79]
	v_mfma_f32_16x16x32_bf16 v[68:71], v[160:163], v[226:229], v[68:71]
	s_setprio 0
	s_setprio 1
	v_mfma_f32_16x16x32_bf16 v[126:129], v[164:167], v[180:183], v[126:129]
	v_mfma_f32_16x16x32_bf16 v[114:117], v[172:175], v[180:183], v[114:117]
	v_mfma_f32_16x16x32_bf16 v[106:109], v[164:167], v[188:191], v[106:109]
	v_mfma_f32_16x16x32_bf16 v[98:101], v[172:175], v[188:191], v[98:101]
	v_mfma_f32_16x16x32_bf16 v[88:91], v[164:167], v[214:217], v[88:91]
	v_mfma_f32_16x16x32_bf16 v[80:83], v[172:175], v[214:217], v[80:83]
	v_mfma_f32_16x16x32_bf16 v[72:75], v[164:167], v[222:225], v[72:75]
	v_mfma_f32_16x16x32_bf16 v[64:67], v[172:175], v[222:225], v[64:67]
	v_mfma_f32_16x16x32_bf16 v[126:129], v[168:171], v[184:187], v[126:129]
	v_mfma_f32_16x16x32_bf16 v[114:117], v[176:179], v[184:187], v[114:117]
	v_mfma_f32_16x16x32_bf16 v[106:109], v[168:171], v[192:195], v[106:109]
	v_mfma_f32_16x16x32_bf16 v[98:101], v[176:179], v[192:195], v[98:101]
	v_mfma_f32_16x16x32_bf16 v[88:91], v[168:171], v[218:221], v[88:91]
	v_mfma_f32_16x16x32_bf16 v[80:83], v[176:179], v[218:221], v[80:83]
	v_mfma_f32_16x16x32_bf16 v[72:75], v[168:171], v[226:229], v[72:75]
	v_mfma_f32_16x16x32_bf16 v[64:67], v[176:179], v[226:229], v[64:67]
	s_setprio 0
	s_barrier
	s_add_i32 s66, s66, s44
	v_lshl_add_u64 v[156:157], s[64:65], 0, v[92:93]
	s_mov_b32 m0, s66
	ds_read_b128 v[180:183], v143 offset:16384
	ds_read_b128 v[184:187], v143 offset:17408
	ds_read_b128 v[188:191], v143 offset:18432
	ds_read_b128 v[192:195], v143 offset:19456
	ds_read_b128 v[214:217], v143 offset:20480
	ds_read_b128 v[218:221], v143 offset:21504
	ds_read_b128 v[222:225], v143 offset:22528
	ds_read_b128 v[226:229], v143 offset:23552
	global_load_lds_dwordx4 v[156:157], off
	s_add_i32 m0, s66, 0x2000
	v_lshl_add_u64 v[230:231], s[64:65], 0, v[134:135]
	s_add_u32 s64, s64, s10
	s_addc_u32 s65, s65, s11
	s_add_i32 s63, s63, s44
	global_load_lds_dwordx4 v[230:231], off
	v_lshl_add_u64 v[232:233], s[64:65], 0, v[92:93]
	s_mov_b32 m0, s63
	v_lshl_add_u64 v[234:235], s[64:65], 0, v[134:135]
	global_load_lds_dwordx4 v[232:233], off
	s_add_i32 m0, s63, 0x2000
	v_lshl_add_u64 v[236:237], s[30:31], 0, v[130:131]
	global_load_lds_dwordx4 v[234:235], off
	s_mov_b32 m0, s47
	v_lshl_add_u64 v[238:239], s[30:31], 0, v[132:133]
	global_load_lds_dwordx4 v[236:237], off
	s_mov_b32 m0, s48
	s_nop 0
	global_load_lds_dwordx4 v[238:239], off
	s_waitcnt vmcnt(8)
	s_waitcnt lgkmcnt(0)
	s_barrier
	s_setprio 1
	s_waitcnt lgkmcnt(0)
	v_mfma_f32_16x16x32_bf16 v[60:63], v[144:147], v[180:183], v[60:63]
	v_mfma_f32_16x16x32_bf16 v[52:55], v[152:155], v[180:183], v[52:55]
	v_mfma_f32_16x16x32_bf16 v[44:47], v[144:147], v[188:191], v[44:47]
	v_mfma_f32_16x16x32_bf16 v[36:39], v[152:155], v[188:191], v[36:39]
	v_mfma_f32_16x16x32_bf16 v[28:31], v[144:147], v[214:217], v[28:31]
	v_mfma_f32_16x16x32_bf16 v[20:23], v[152:155], v[214:217], v[20:23]
	v_mfma_f32_16x16x32_bf16 v[12:15], v[144:147], v[222:225], v[12:15]
	v_mfma_f32_16x16x32_bf16 v[4:7], v[152:155], v[222:225], v[4:7]
	v_mfma_f32_16x16x32_bf16 v[60:63], v[148:151], v[184:187], v[60:63]
	v_mfma_f32_16x16x32_bf16 v[52:55], v[160:163], v[184:187], v[52:55]
	v_mfma_f32_16x16x32_bf16 v[44:47], v[148:151], v[192:195], v[44:47]
	v_mfma_f32_16x16x32_bf16 v[36:39], v[160:163], v[192:195], v[36:39]
	v_mfma_f32_16x16x32_bf16 v[28:31], v[148:151], v[218:221], v[28:31]
	v_mfma_f32_16x16x32_bf16 v[20:23], v[160:163], v[218:221], v[20:23]
	v_mfma_f32_16x16x32_bf16 v[12:15], v[148:151], v[226:229], v[12:15]
	v_mfma_f32_16x16x32_bf16 v[4:7], v[160:163], v[226:229], v[4:7]
	s_setprio 0
	s_setprio 1
	v_mfma_f32_16x16x32_bf16 v[56:59], v[164:167], v[180:183], v[56:59]
	v_mfma_f32_16x16x32_bf16 v[48:51], v[172:175], v[180:183], v[48:51]
	v_mfma_f32_16x16x32_bf16 v[40:43], v[164:167], v[188:191], v[40:43]
	v_mfma_f32_16x16x32_bf16 v[32:35], v[172:175], v[188:191], v[32:35]
	v_mfma_f32_16x16x32_bf16 v[24:27], v[164:167], v[214:217], v[24:27]
	v_mfma_f32_16x16x32_bf16 v[16:19], v[172:175], v[214:217], v[16:19]
	v_mfma_f32_16x16x32_bf16 v[8:11], v[164:167], v[222:225], v[8:11]
	v_mfma_f32_16x16x32_bf16 v[0:3], v[172:175], v[222:225], v[0:3]
	v_mfma_f32_16x16x32_bf16 v[56:59], v[168:171], v[184:187], v[56:59]
	v_mfma_f32_16x16x32_bf16 v[48:51], v[176:179], v[184:187], v[48:51]
	v_mfma_f32_16x16x32_bf16 v[40:43], v[168:171], v[192:195], v[40:43]
	v_mfma_f32_16x16x32_bf16 v[32:35], v[176:179], v[192:195], v[32:35]
	v_mfma_f32_16x16x32_bf16 v[24:27], v[168:171], v[218:221], v[24:27]
	v_mfma_f32_16x16x32_bf16 v[16:19], v[176:179], v[218:221], v[16:19]
	v_mfma_f32_16x16x32_bf16 v[8:11], v[168:171], v[226:229], v[8:11]
	v_mfma_f32_16x16x32_bf16 v[0:3], v[176:179], v[226:229], v[0:3]
	s_setprio 0
	s_barrier
	s_add_i32 s63, 0, 0x18000
	v_add_u32_e32 v159, s63, v141
	s_add_i32 s64, 0, 0x1c000
	ds_read_b128 v[144:147], v159
	ds_read_b128 v[148:151], v159 offset:1024
	ds_read_b128 v[152:155], v159 offset:2048
	ds_read_b128 v[160:163], v159 offset:3072
	v_add_u32_e32 v159, s64, v141
	ds_read_b128 v[164:167], v159
	ds_read_b128 v[168:171], v159 offset:1024
	ds_read_b128 v[172:175], v159 offset:2048
	ds_read_b128 v[176:179], v159 offset:3072
	s_add_u32 s30, s30, s14
	s_addc_u32 s31, s31, s15
	s_mov_b32 m0, s49
	v_lshl_add_u64 v[240:241], s[30:31], 0, v[130:131]
	ds_read_b128 v[180:183], v143 offset:32768
	ds_read_b128 v[184:187], v143 offset:33792
	ds_read_b128 v[188:191], v143 offset:34816
	ds_read_b128 v[192:195], v143 offset:35840
	ds_read_b128 v[214:217], v143 offset:36864
	ds_read_b128 v[218:221], v143 offset:37888
	ds_read_b128 v[222:225], v143 offset:38912
	ds_read_b128 v[226:229], v143 offset:39936
	global_load_lds_dwordx4 v[240:241], off
	v_lshl_add_u64 v[240:241], s[30:31], 0, v[132:133]
	s_mov_b32 m0, s50
	s_nop 0
	global_load_lds_dwordx4 v[240:241], off
	s_waitcnt vmcnt(8)
	s_waitcnt lgkmcnt(0)
	s_barrier
	s_setprio 1
	s_waitcnt lgkmcnt(0)
	v_mfma_f32_16x16x32_bf16 v[122:125], v[144:147], v[180:183], v[122:125]
	v_mfma_f32_16x16x32_bf16 v[118:121], v[152:155], v[180:183], v[118:121]
	v_mfma_f32_16x16x32_bf16 v[110:113], v[144:147], v[188:191], v[110:113]
	v_mfma_f32_16x16x32_bf16 v[102:105], v[152:155], v[188:191], v[102:105]
	v_mfma_f32_16x16x32_bf16 v[94:97], v[144:147], v[214:217], v[94:97]
	v_mfma_f32_16x16x32_bf16 v[84:87], v[152:155], v[214:217], v[84:87]
	v_mfma_f32_16x16x32_bf16 v[76:79], v[144:147], v[222:225], v[76:79]
	v_mfma_f32_16x16x32_bf16 v[68:71], v[152:155], v[222:225], v[68:71]
	v_mfma_f32_16x16x32_bf16 v[122:125], v[148:151], v[184:187], v[122:125]
	v_mfma_f32_16x16x32_bf16 v[118:121], v[160:163], v[184:187], v[118:121]
	v_mfma_f32_16x16x32_bf16 v[110:113], v[148:151], v[192:195], v[110:113]
	v_mfma_f32_16x16x32_bf16 v[102:105], v[160:163], v[192:195], v[102:105]
	v_mfma_f32_16x16x32_bf16 v[94:97], v[148:151], v[218:221], v[94:97]
	v_mfma_f32_16x16x32_bf16 v[84:87], v[160:163], v[218:221], v[84:87]
	v_mfma_f32_16x16x32_bf16 v[76:79], v[148:151], v[226:229], v[76:79]
	v_mfma_f32_16x16x32_bf16 v[68:71], v[160:163], v[226:229], v[68:71]
	s_setprio 0
	s_setprio 1
	v_mfma_f32_16x16x32_bf16 v[126:129], v[164:167], v[180:183], v[126:129]
	v_mfma_f32_16x16x32_bf16 v[114:117], v[172:175], v[180:183], v[114:117]
	v_mfma_f32_16x16x32_bf16 v[106:109], v[164:167], v[188:191], v[106:109]
	v_mfma_f32_16x16x32_bf16 v[98:101], v[172:175], v[188:191], v[98:101]
	v_mfma_f32_16x16x32_bf16 v[88:91], v[164:167], v[214:217], v[88:91]
	v_mfma_f32_16x16x32_bf16 v[80:83], v[172:175], v[214:217], v[80:83]
	v_mfma_f32_16x16x32_bf16 v[72:75], v[164:167], v[222:225], v[72:75]
	v_mfma_f32_16x16x32_bf16 v[64:67], v[172:175], v[222:225], v[64:67]
	v_mfma_f32_16x16x32_bf16 v[126:129], v[168:171], v[184:187], v[126:129]
	v_mfma_f32_16x16x32_bf16 v[114:117], v[176:179], v[184:187], v[114:117]
	v_mfma_f32_16x16x32_bf16 v[106:109], v[168:171], v[192:195], v[106:109]
	v_mfma_f32_16x16x32_bf16 v[98:101], v[176:179], v[192:195], v[98:101]
	v_mfma_f32_16x16x32_bf16 v[88:91], v[168:171], v[218:221], v[88:91]
	v_mfma_f32_16x16x32_bf16 v[80:83], v[176:179], v[218:221], v[80:83]
	v_mfma_f32_16x16x32_bf16 v[72:75], v[168:171], v[226:229], v[72:75]
	v_mfma_f32_16x16x32_bf16 v[64:67], v[176:179], v[226:229], v[64:67]
	s_setprio 0
	s_barrier
	s_add_i32 s30, s63, s44
	v_lshl_add_u64 v[156:157], v[156:157], 0, s[80:81]
	s_mov_b32 m0, s30
	ds_read_b128 v[180:183], v143 offset:49152
	ds_read_b128 v[184:187], v143 offset:50176
	ds_read_b128 v[188:191], v143 offset:51200
	ds_read_b128 v[192:195], v143 offset:52224
	ds_read_b128 v[214:217], v143 offset:53248
	ds_read_b128 v[218:221], v143 offset:54272
	ds_read_b128 v[222:225], v143 offset:55296
	ds_read_b128 v[226:229], v143 offset:56320
	global_load_lds_dwordx4 v[156:157], off
	v_lshl_add_u64 v[156:157], v[230:231], 0, s[80:81]
	s_add_i32 m0, s30, 0x2000
	s_add_i32 s30, s64, s44
	global_load_lds_dwordx4 v[156:157], off
	v_lshl_add_u64 v[156:157], v[232:233], 0, s[80:81]
	s_mov_b32 m0, s30
	s_nop 0
	global_load_lds_dwordx4 v[156:157], off
	v_lshl_add_u64 v[156:157], v[234:235], 0, s[80:81]
	s_add_i32 m0, s30, 0x2000
	s_nop 0
	global_load_lds_dwordx4 v[156:157], off
	v_lshl_add_u64 v[156:157], v[236:237], 0, s[80:81]
	s_mov_b32 m0, s51
	s_nop 0
	global_load_lds_dwordx4 v[156:157], off
	v_lshl_add_u64 v[156:157], v[238:239], 0, s[80:81]
	s_mov_b32 m0, s52
	s_nop 0
	global_load_lds_dwordx4 v[156:157], off
	s_waitcnt vmcnt(8)
	s_waitcnt lgkmcnt(0)
	s_barrier
	s_setprio 1
	s_waitcnt lgkmcnt(0)
	v_mfma_f32_16x16x32_bf16 v[60:63], v[144:147], v[180:183], v[60:63]
	v_mfma_f32_16x16x32_bf16 v[52:55], v[152:155], v[180:183], v[52:55]
	v_mfma_f32_16x16x32_bf16 v[44:47], v[144:147], v[188:191], v[44:47]
	v_mfma_f32_16x16x32_bf16 v[36:39], v[152:155], v[188:191], v[36:39]
	v_mfma_f32_16x16x32_bf16 v[28:31], v[144:147], v[214:217], v[28:31]
	v_mfma_f32_16x16x32_bf16 v[20:23], v[152:155], v[214:217], v[20:23]
	v_mfma_f32_16x16x32_bf16 v[12:15], v[144:147], v[222:225], v[12:15]
	v_mfma_f32_16x16x32_bf16 v[4:7], v[152:155], v[222:225], v[4:7]
	v_mfma_f32_16x16x32_bf16 v[60:63], v[148:151], v[184:187], v[60:63]
	v_mfma_f32_16x16x32_bf16 v[52:55], v[160:163], v[184:187], v[52:55]
	v_mfma_f32_16x16x32_bf16 v[44:47], v[148:151], v[192:195], v[44:47]
	v_mfma_f32_16x16x32_bf16 v[36:39], v[160:163], v[192:195], v[36:39]
	v_mfma_f32_16x16x32_bf16 v[28:31], v[148:151], v[218:221], v[28:31]
	v_mfma_f32_16x16x32_bf16 v[20:23], v[160:163], v[218:221], v[20:23]
	v_mfma_f32_16x16x32_bf16 v[12:15], v[148:151], v[226:229], v[12:15]
	v_mfma_f32_16x16x32_bf16 v[4:7], v[160:163], v[226:229], v[4:7]
	s_setprio 0
	s_setprio 1
	v_mfma_f32_16x16x32_bf16 v[56:59], v[164:167], v[180:183], v[56:59]
	v_mfma_f32_16x16x32_bf16 v[48:51], v[172:175], v[180:183], v[48:51]
	v_mfma_f32_16x16x32_bf16 v[40:43], v[164:167], v[188:191], v[40:43]
	v_mfma_f32_16x16x32_bf16 v[32:35], v[172:175], v[188:191], v[32:35]
	v_mfma_f32_16x16x32_bf16 v[24:27], v[164:167], v[214:217], v[24:27]
	v_mfma_f32_16x16x32_bf16 v[16:19], v[172:175], v[214:217], v[16:19]
	v_mfma_f32_16x16x32_bf16 v[8:11], v[164:167], v[222:225], v[8:11]
	v_mfma_f32_16x16x32_bf16 v[0:3], v[172:175], v[222:225], v[0:3]
	v_mfma_f32_16x16x32_bf16 v[56:59], v[168:171], v[184:187], v[56:59]
	v_mfma_f32_16x16x32_bf16 v[48:51], v[176:179], v[184:187], v[48:51]
	v_mfma_f32_16x16x32_bf16 v[40:43], v[168:171], v[192:195], v[40:43]
	v_mfma_f32_16x16x32_bf16 v[32:35], v[176:179], v[192:195], v[32:35]
	v_mfma_f32_16x16x32_bf16 v[24:27], v[168:171], v[218:221], v[24:27]
	v_mfma_f32_16x16x32_bf16 v[16:19], v[176:179], v[218:221], v[16:19]
	v_mfma_f32_16x16x32_bf16 v[8:11], v[168:171], v[226:229], v[8:11]
	v_mfma_f32_16x16x32_bf16 v[0:3], v[176:179], v[226:229], v[0:3]
	s_setprio 0
	s_add_u32 s28, s28, 0x100
	s_addc_u32 s29, s29, 0
	s_add_u32 s60, s60, 0x100
	s_addc_u32 s61, s61, 0
	s_cmp_ge_i32 s62, s53
	s_mov_b32 s30, s62
	s_cbranch_scc1 .Lrot9_exit
	s_add_i32 s62, s30, 2
	s_add_u32 s63, s28, 0x80
	s_addc_u32 s31, s29, 0
	s_add_i32 s66, 0, 0x10000
	s_cmp_eq_u32 s54, s30
	s_cselect_b32 s31, s7, s31
	s_cselect_b32 s30, s6, s63
	v_add_u32_e32 v156, s66, v141
	s_cselect_b32 s65, s27, s61
	s_cselect_b32 s64, s26, s60
	s_add_i32 s63, 0, 0x14000
	s_barrier
	s_branch .Lrot9_body
.Lrot9_exit:
	s_barrier

.Lrot8_body:
	ds_read_b128 v[140:143], v152
	ds_read_b128 v[144:147], v152 offset:1024
	ds_read_b128 v[148:151], v152 offset:2048
	ds_read_b128 v[152:155], v152 offset:3072
	ds_read_b128 v[160:163], v156
	ds_read_b128 v[168:171], v156 offset:1024
	ds_read_b128 v[172:175], v156 offset:2048
	ds_read_b128 v[176:179], v156 offset:3072
	v_lshl_add_u64 v[156:157], s[28:29], 0, v[136:137]
	s_add_i32 m0, s46, 0xc000
	ds_read_b128 v[180:183], v166
	ds_read_b128 v[184:187], v166 offset:1024
	ds_read_b128 v[188:191], v166 offset:2048
	ds_read_b128 v[192:195], v166 offset:3072
	ds_read_b128 v[214:217], v166 offset:4096
	ds_read_b128 v[218:221], v166 offset:5120
	ds_read_b128 v[222:225], v166 offset:6144
	ds_read_b128 v[226:229], v166 offset:7168
	global_load_lds_dwordx4 v[156:157], off
	v_lshl_add_u64 v[156:157], s[28:29], 0, v[138:139]
	s_add_i32 m0, s46, 0xe000
	s_nop 0
	global_load_lds_dwordx4 v[156:157], off
	s_waitcnt vmcnt(8)
	s_waitcnt lgkmcnt(0)
	s_barrier
	s_setprio 1
	s_waitcnt lgkmcnt(0)
	v_mfma_f32_16x16x32_bf16 v[126:129], v[140:143], v[180:183], v[126:129]
	v_mfma_f32_16x16x32_bf16 v[122:125], v[148:151], v[180:183], v[122:125]
	v_mfma_f32_16x16x32_bf16 v[110:113], v[140:143], v[188:191], v[110:113]
	v_mfma_f32_16x16x32_bf16 v[106:109], v[148:151], v[188:191], v[106:109]
	v_mfma_f32_16x16x32_bf16 v[94:97], v[140:143], v[214:217], v[94:97]
	v_mfma_f32_16x16x32_bf16 v[88:91], v[148:151], v[214:217], v[88:91]
	v_mfma_f32_16x16x32_bf16 v[76:79], v[140:143], v[222:225], v[76:79]
	v_mfma_f32_16x16x32_bf16 v[72:75], v[148:151], v[222:225], v[72:75]
	v_mfma_f32_16x16x32_bf16 v[126:129], v[144:147], v[184:187], v[126:129]
	v_mfma_f32_16x16x32_bf16 v[122:125], v[152:155], v[184:187], v[122:125]
	v_mfma_f32_16x16x32_bf16 v[110:113], v[144:147], v[192:195], v[110:113]
	v_mfma_f32_16x16x32_bf16 v[106:109], v[152:155], v[192:195], v[106:109]
	v_mfma_f32_16x16x32_bf16 v[94:97], v[144:147], v[218:221], v[94:97]
	v_mfma_f32_16x16x32_bf16 v[88:91], v[152:155], v[218:221], v[88:91]
	v_mfma_f32_16x16x32_bf16 v[76:79], v[144:147], v[226:229], v[76:79]
	v_mfma_f32_16x16x32_bf16 v[72:75], v[152:155], v[226:229], v[72:75]
	s_setprio 0
	s_setprio 1
	v_mfma_f32_16x16x32_bf16 v[118:121], v[160:163], v[180:183], v[118:121]
	v_mfma_f32_16x16x32_bf16 v[114:117], v[172:175], v[180:183], v[114:117]
	v_mfma_f32_16x16x32_bf16 v[102:105], v[160:163], v[188:191], v[102:105]
	v_mfma_f32_16x16x32_bf16 v[98:101], v[172:175], v[188:191], v[98:101]
	v_mfma_f32_16x16x32_bf16 v[84:87], v[160:163], v[214:217], v[84:87]
	v_mfma_f32_16x16x32_bf16 v[80:83], v[172:175], v[214:217], v[80:83]
	v_mfma_f32_16x16x32_bf16 v[68:71], v[160:163], v[222:225], v[68:71]
	v_mfma_f32_16x16x32_bf16 v[64:67], v[172:175], v[222:225], v[64:67]
	v_mfma_f32_16x16x32_bf16 v[118:121], v[168:171], v[184:187], v[118:121]
	v_mfma_f32_16x16x32_bf16 v[114:117], v[176:179], v[184:187], v[114:117]
	v_mfma_f32_16x16x32_bf16 v[102:105], v[168:171], v[192:195], v[102:105]
	v_mfma_f32_16x16x32_bf16 v[98:101], v[176:179], v[192:195], v[98:101]
	v_mfma_f32_16x16x32_bf16 v[84:87], v[168:171], v[218:221], v[84:87]
	v_mfma_f32_16x16x32_bf16 v[80:83], v[176:179], v[218:221], v[80:83]
	v_mfma_f32_16x16x32_bf16 v[68:71], v[168:171], v[226:229], v[68:71]
	v_mfma_f32_16x16x32_bf16 v[64:67], v[176:179], v[226:229], v[64:67]
	s_setprio 0
	s_barrier
	s_add_i32 s66, s66, s41
	v_lshl_add_u64 v[156:157], s[64:65], 0, v[92:93]
	s_mov_b32 m0, s66
	ds_read_b128 v[180:183], v166 offset:16384
	ds_read_b128 v[184:187], v166 offset:17408
	ds_read_b128 v[188:191], v166 offset:18432
	ds_read_b128 v[192:195], v166 offset:19456
	ds_read_b128 v[214:217], v166 offset:20480
	ds_read_b128 v[218:221], v166 offset:21504
	ds_read_b128 v[222:225], v166 offset:22528
	ds_read_b128 v[226:229], v166 offset:23552
	global_load_lds_dwordx4 v[156:157], off
	s_add_i32 m0, s66, 0x2000
	v_lshl_add_u64 v[230:231], s[64:65], 0, v[134:135]
	s_add_u32 s64, s64, s10
	s_addc_u32 s65, s65, s11
	s_add_i32 s66, s67, s41
	global_load_lds_dwordx4 v[230:231], off
	v_lshl_add_u64 v[232:233], s[64:65], 0, v[92:93]
	s_mov_b32 m0, s66
	v_lshl_add_u64 v[234:235], s[64:65], 0, v[134:135]
	global_load_lds_dwordx4 v[232:233], off
	s_add_i32 m0, s66, 0x2000
	v_lshl_add_u64 v[236:237], s[30:31], 0, v[130:131]
	global_load_lds_dwordx4 v[234:235], off
	s_mov_b32 m0, s46
	v_lshl_add_u64 v[238:239], s[30:31], 0, v[132:133]
	global_load_lds_dwordx4 v[236:237], off
	s_mov_b32 m0, s47
	s_nop 0
	global_load_lds_dwordx4 v[238:239], off
	s_waitcnt vmcnt(8)
	s_waitcnt lgkmcnt(0)
	s_barrier
	s_setprio 1
	s_waitcnt lgkmcnt(0)
	v_mfma_f32_16x16x32_bf16 v[60:63], v[140:143], v[180:183], v[60:63]
	v_mfma_f32_16x16x32_bf16 v[56:59], v[148:151], v[180:183], v[56:59]
	v_mfma_f32_16x16x32_bf16 v[44:47], v[140:143], v[188:191], v[44:47]
	v_mfma_f32_16x16x32_bf16 v[40:43], v[148:151], v[188:191], v[40:43]
	v_mfma_f32_16x16x32_bf16 v[28:31], v[140:143], v[214:217], v[28:31]
	v_mfma_f32_16x16x32_bf16 v[24:27], v[148:151], v[214:217], v[24:27]
	v_mfma_f32_16x16x32_bf16 v[12:15], v[140:143], v[222:225], v[12:15]
	v_mfma_f32_16x16x32_bf16 v[8:11], v[148:151], v[222:225], v[8:11]
	v_mfma_f32_16x16x32_bf16 v[60:63], v[144:147], v[184:187], v[60:63]
	v_mfma_f32_16x16x32_bf16 v[56:59], v[152:155], v[184:187], v[56:59]
	v_mfma_f32_16x16x32_bf16 v[44:47], v[144:147], v[192:195], v[44:47]
	v_mfma_f32_16x16x32_bf16 v[40:43], v[152:155], v[192:195], v[40:43]
	v_mfma_f32_16x16x32_bf16 v[28:31], v[144:147], v[218:221], v[28:31]
	v_mfma_f32_16x16x32_bf16 v[24:27], v[152:155], v[218:221], v[24:27]
	v_mfma_f32_16x16x32_bf16 v[12:15], v[144:147], v[226:229], v[12:15]
	v_mfma_f32_16x16x32_bf16 v[8:11], v[152:155], v[226:229], v[8:11]
	s_setprio 0
	s_setprio 1
	v_mfma_f32_16x16x32_bf16 v[52:55], v[160:163], v[180:183], v[52:55]
	v_mfma_f32_16x16x32_bf16 v[48:51], v[172:175], v[180:183], v[48:51]
	v_mfma_f32_16x16x32_bf16 v[36:39], v[160:163], v[188:191], v[36:39]
	v_mfma_f32_16x16x32_bf16 v[32:35], v[172:175], v[188:191], v[32:35]
	v_mfma_f32_16x16x32_bf16 v[20:23], v[160:163], v[214:217], v[20:23]
	v_mfma_f32_16x16x32_bf16 v[16:19], v[172:175], v[214:217], v[16:19]
	v_mfma_f32_16x16x32_bf16 v[4:7], v[160:163], v[222:225], v[4:7]
	v_mfma_f32_16x16x32_bf16 v[0:3], v[172:175], v[222:225], v[0:3]
	v_mfma_f32_16x16x32_bf16 v[52:55], v[168:171], v[184:187], v[52:55]
	v_mfma_f32_16x16x32_bf16 v[48:51], v[176:179], v[184:187], v[48:51]
	v_mfma_f32_16x16x32_bf16 v[36:39], v[168:171], v[192:195], v[36:39]
	v_mfma_f32_16x16x32_bf16 v[32:35], v[176:179], v[192:195], v[32:35]
	v_mfma_f32_16x16x32_bf16 v[20:23], v[168:171], v[218:221], v[20:23]
	v_mfma_f32_16x16x32_bf16 v[16:19], v[176:179], v[218:221], v[16:19]
	v_mfma_f32_16x16x32_bf16 v[4:7], v[168:171], v[226:229], v[4:7]
	v_mfma_f32_16x16x32_bf16 v[0:3], v[176:179], v[226:229], v[0:3]
	s_setprio 0
	s_barrier
	s_add_i32 s64, 0, 0x18000
	s_add_i32 s65, 0, 0x1c000
	v_add_u32_e32 v152, s64, v164
	v_add_u32_e32 v167, s65, v164
	ds_read_b128 v[140:143], v152
	ds_read_b128 v[144:147], v152 offset:1024
	ds_read_b128 v[148:151], v152 offset:2048
	ds_read_b128 v[152:155], v152 offset:3072
	ds_read_b128 v[160:163], v167
	ds_read_b128 v[168:171], v167 offset:1024
	ds_read_b128 v[172:175], v167 offset:2048
	ds_read_b128 v[176:179], v167 offset:3072
	s_add_u32 s30, s30, s14
	s_addc_u32 s31, s31, s15
	s_mov_b32 m0, s48
	v_lshl_add_u64 v[240:241], s[30:31], 0, v[130:131]
	ds_read_b128 v[180:183], v166 offset:32768
	ds_read_b128 v[184:187], v166 offset:33792
	ds_read_b128 v[188:191], v166 offset:34816
	ds_read_b128 v[192:195], v166 offset:35840
	ds_read_b128 v[214:217], v166 offset:36864
	ds_read_b128 v[218:221], v166 offset:37888
	ds_read_b128 v[222:225], v166 offset:38912
	ds_read_b128 v[226:229], v166 offset:39936
	global_load_lds_dwordx4 v[240:241], off
	v_lshl_add_u64 v[240:241], s[30:31], 0, v[132:133]
	s_mov_b32 m0, s49
	s_nop 0
	global_load_lds_dwordx4 v[240:241], off
	s_waitcnt vmcnt(8)
	s_waitcnt lgkmcnt(0)
	s_barrier
	s_setprio 1
	s_waitcnt lgkmcnt(0)
	v_mfma_f32_16x16x32_bf16 v[126:129], v[140:143], v[180:183], v[126:129]
	v_mfma_f32_16x16x32_bf16 v[122:125], v[148:151], v[180:183], v[122:125]
	v_mfma_f32_16x16x32_bf16 v[110:113], v[140:143], v[188:191], v[110:113]
	v_mfma_f32_16x16x32_bf16 v[106:109], v[148:151], v[188:191], v[106:109]
	v_mfma_f32_16x16x32_bf16 v[94:97], v[140:143], v[214:217], v[94:97]
	v_mfma_f32_16x16x32_bf16 v[88:91], v[148:151], v[214:217], v[88:91]
	v_mfma_f32_16x16x32_bf16 v[76:79], v[140:143], v[222:225], v[76:79]
	v_mfma_f32_16x16x32_bf16 v[72:75], v[148:151], v[222:225], v[72:75]
	v_mfma_f32_16x16x32_bf16 v[126:129], v[144:147], v[184:187], v[126:129]
	v_mfma_f32_16x16x32_bf16 v[122:125], v[152:155], v[184:187], v[122:125]
	v_mfma_f32_16x16x32_bf16 v[110:113], v[144:147], v[192:195], v[110:113]
	v_mfma_f32_16x16x32_bf16 v[106:109], v[152:155], v[192:195], v[106:109]
	v_mfma_f32_16x16x32_bf16 v[94:97], v[144:147], v[218:221], v[94:97]
	v_mfma_f32_16x16x32_bf16 v[88:91], v[152:155], v[218:221], v[88:91]
	v_mfma_f32_16x16x32_bf16 v[76:79], v[144:147], v[226:229], v[76:79]
	v_mfma_f32_16x16x32_bf16 v[72:75], v[152:155], v[226:229], v[72:75]
	s_setprio 0
	s_setprio 1
	v_mfma_f32_16x16x32_bf16 v[118:121], v[160:163], v[180:183], v[118:121]
	v_mfma_f32_16x16x32_bf16 v[114:117], v[172:175], v[180:183], v[114:117]
	v_mfma_f32_16x16x32_bf16 v[102:105], v[160:163], v[188:191], v[102:105]
	v_mfma_f32_16x16x32_bf16 v[98:101], v[172:175], v[188:191], v[98:101]
	v_mfma_f32_16x16x32_bf16 v[84:87], v[160:163], v[214:217], v[84:87]
	v_mfma_f32_16x16x32_bf16 v[80:83], v[172:175], v[214:217], v[80:83]
	v_mfma_f32_16x16x32_bf16 v[68:71], v[160:163], v[222:225], v[68:71]
	v_mfma_f32_16x16x32_bf16 v[64:67], v[172:175], v[222:225], v[64:67]
	v_mfma_f32_16x16x32_bf16 v[118:121], v[168:171], v[184:187], v[118:121]
	v_mfma_f32_16x16x32_bf16 v[114:117], v[176:179], v[184:187], v[114:117]
	v_mfma_f32_16x16x32_bf16 v[102:105], v[168:171], v[192:195], v[102:105]
	v_mfma_f32_16x16x32_bf16 v[98:101], v[176:179], v[192:195], v[98:101]
	v_mfma_f32_16x16x32_bf16 v[84:87], v[168:171], v[218:221], v[84:87]
	v_mfma_f32_16x16x32_bf16 v[80:83], v[176:179], v[218:221], v[80:83]
	v_mfma_f32_16x16x32_bf16 v[68:71], v[168:171], v[226:229], v[68:71]
	v_mfma_f32_16x16x32_bf16 v[64:67], v[176:179], v[226:229], v[64:67]
	s_setprio 0
	s_barrier
	s_add_i32 s30, s64, s41
	v_lshl_add_u64 v[156:157], v[156:157], 0, s[80:81]
	s_mov_b32 m0, s30
	ds_read_b128 v[180:183], v166 offset:49152
	ds_read_b128 v[184:187], v166 offset:50176
	ds_read_b128 v[188:191], v166 offset:51200
	ds_read_b128 v[192:195], v166 offset:52224
	ds_read_b128 v[214:217], v166 offset:53248
	ds_read_b128 v[218:221], v166 offset:54272
	ds_read_b128 v[222:225], v166 offset:55296
	ds_read_b128 v[226:229], v166 offset:56320
	global_load_lds_dwordx4 v[156:157], off
	v_lshl_add_u64 v[156:157], v[230:231], 0, s[80:81]
	s_add_i32 m0, s30, 0x2000
	s_add_i32 s30, s65, s41
	global_load_lds_dwordx4 v[156:157], off
	v_lshl_add_u64 v[156:157], v[232:233], 0, s[80:81]
	s_mov_b32 m0, s30
	s_nop 0
	global_load_lds_dwordx4 v[156:157], off
	v_lshl_add_u64 v[156:157], v[234:235], 0, s[80:81]
	s_add_i32 m0, s30, 0x2000
	s_nop 0
	global_load_lds_dwordx4 v[156:157], off
	v_lshl_add_u64 v[156:157], v[236:237], 0, s[80:81]
	s_mov_b32 m0, s53
	s_nop 0
	global_load_lds_dwordx4 v[156:157], off
	v_lshl_add_u64 v[156:157], v[238:239], 0, s[80:81]
	s_mov_b32 m0, s54
	s_nop 0
	global_load_lds_dwordx4 v[156:157], off
	s_waitcnt vmcnt(8)
	s_waitcnt lgkmcnt(0)
	s_barrier
	s_setprio 1
	s_waitcnt lgkmcnt(0)
	v_mfma_f32_16x16x32_bf16 v[60:63], v[140:143], v[180:183], v[60:63]
	v_mfma_f32_16x16x32_bf16 v[56:59], v[148:151], v[180:183], v[56:59]
	v_mfma_f32_16x16x32_bf16 v[44:47], v[140:143], v[188:191], v[44:47]
	v_mfma_f32_16x16x32_bf16 v[40:43], v[148:151], v[188:191], v[40:43]
	v_mfma_f32_16x16x32_bf16 v[28:31], v[140:143], v[214:217], v[28:31]
	v_mfma_f32_16x16x32_bf16 v[24:27], v[148:151], v[214:217], v[24:27]
	v_mfma_f32_16x16x32_bf16 v[12:15], v[140:143], v[222:225], v[12:15]
	v_mfma_f32_16x16x32_bf16 v[8:11], v[148:151], v[222:225], v[8:11]
	v_mfma_f32_16x16x32_bf16 v[60:63], v[144:147], v[184:187], v[60:63]
	v_mfma_f32_16x16x32_bf16 v[56:59], v[152:155], v[184:187], v[56:59]
	v_mfma_f32_16x16x32_bf16 v[44:47], v[144:147], v[192:195], v[44:47]
	v_mfma_f32_16x16x32_bf16 v[40:43], v[152:155], v[192:195], v[40:43]
	v_mfma_f32_16x16x32_bf16 v[28:31], v[144:147], v[218:221], v[28:31]
	v_mfma_f32_16x16x32_bf16 v[24:27], v[152:155], v[218:221], v[24:27]
	v_mfma_f32_16x16x32_bf16 v[12:15], v[144:147], v[226:229], v[12:15]
	v_mfma_f32_16x16x32_bf16 v[8:11], v[152:155], v[226:229], v[8:11]
	s_setprio 0
	s_setprio 1
	v_mfma_f32_16x16x32_bf16 v[52:55], v[160:163], v[180:183], v[52:55]
	v_mfma_f32_16x16x32_bf16 v[48:51], v[172:175], v[180:183], v[48:51]
	v_mfma_f32_16x16x32_bf16 v[36:39], v[160:163], v[188:191], v[36:39]
	v_mfma_f32_16x16x32_bf16 v[32:35], v[172:175], v[188:191], v[32:35]
	v_mfma_f32_16x16x32_bf16 v[20:23], v[160:163], v[214:217], v[20:23]
	v_mfma_f32_16x16x32_bf16 v[16:19], v[172:175], v[214:217], v[16:19]
	v_mfma_f32_16x16x32_bf16 v[4:7], v[160:163], v[222:225], v[4:7]
	v_mfma_f32_16x16x32_bf16 v[0:3], v[172:175], v[222:225], v[0:3]
	v_mfma_f32_16x16x32_bf16 v[52:55], v[168:171], v[184:187], v[52:55]
	v_mfma_f32_16x16x32_bf16 v[48:51], v[176:179], v[184:187], v[48:51]
	v_mfma_f32_16x16x32_bf16 v[36:39], v[168:171], v[192:195], v[36:39]
	v_mfma_f32_16x16x32_bf16 v[32:35], v[176:179], v[192:195], v[32:35]
	v_mfma_f32_16x16x32_bf16 v[20:23], v[168:171], v[218:221], v[20:23]
	v_mfma_f32_16x16x32_bf16 v[16:19], v[176:179], v[218:221], v[16:19]
	v_mfma_f32_16x16x32_bf16 v[4:7], v[168:171], v[226:229], v[4:7]
	v_mfma_f32_16x16x32_bf16 v[0:3], v[176:179], v[226:229], v[0:3]
	s_setprio 0
	s_add_u32 s28, s28, 0x100
	s_addc_u32 s29, s29, 0
	s_add_u32 s61, s61, 0x100
	s_addc_u32 s62, s62, 0
	s_cmp_ge_i32 s63, s52
	s_mov_b32 s30, s63
	s_cbranch_scc1 .Lrot8_exit
	s_add_i32 s63, s30, 2
	s_add_u32 s64, s28, 0x80
	s_addc_u32 s31, s29, 0
	s_add_i32 s66, 0, 0x10000
	s_cmp_eq_u32 s55, s30
	s_cselect_b32 s31, s7, s31
	s_cselect_b32 s30, s6, s64
	s_cselect_b32 s65, s27, s62
	s_cselect_b32 s64, s26, s61
	s_add_i32 s67, 0, 0x14000
	v_add_u32_e32 v152, s66, v164
	v_add_u32_e32 v156, s67, v164
	s_barrier
	s_branch .Lrot8_body
.Lrot8_exit:
	s_barrier
	s_movk_i32 s67, 0x4000

.Lrot7_body:
	ds_read_b128 v[152:155], v92
	ds_read_b128 v[160:163], v92 offset:1024
	ds_read_b128 v[164:167], v92 offset:2048
	ds_read_b128 v[168:171], v92 offset:3072
	v_add_u32_e32 v92, s37, v141
	ds_read_b128 v[172:175], v92
	ds_read_b128 v[176:179], v92 offset:1024
	ds_read_b128 v[180:183], v92 offset:2048
	ds_read_b128 v[184:187], v92 offset:3072
	v_lshl_add_u64 v[156:157], s[8:9], 0, v[148:149]
	s_add_i32 m0, s54, 0xc000
	ds_read_b128 v[188:191], v143
	ds_read_b128 v[192:195], v143 offset:1024
	ds_read_b128 v[214:217], v143 offset:2048
	ds_read_b128 v[218:221], v143 offset:3072
	ds_read_b128 v[222:225], v143 offset:4096
	ds_read_b128 v[226:229], v143 offset:5120
	ds_read_b128 v[230:233], v143 offset:6144
	ds_read_b128 v[234:237], v143 offset:7168
	global_load_lds_dwordx4 v[156:157], off
	v_lshl_add_u64 v[156:157], s[8:9], 0, v[150:151]
	s_add_i32 m0, s54, 0xe000
	s_nop 0
	global_load_lds_dwordx4 v[156:157], off
	s_waitcnt vmcnt(8)
	s_waitcnt lgkmcnt(0)
	s_barrier
	s_setprio 1
	s_waitcnt lgkmcnt(0)
	v_mfma_f32_16x16x32_bf16 v[126:129], v[152:155], v[188:191], v[126:129]
	v_mfma_f32_16x16x32_bf16 v[122:125], v[164:167], v[188:191], v[122:125]
	v_mfma_f32_16x16x32_bf16 v[118:121], v[152:155], v[214:217], v[118:121]
	v_mfma_f32_16x16x32_bf16 v[114:117], v[164:167], v[214:217], v[114:117]
	v_mfma_f32_16x16x32_bf16 v[110:113], v[152:155], v[222:225], v[110:113]
	v_mfma_f32_16x16x32_bf16 v[106:109], v[164:167], v[222:225], v[106:109]
	v_mfma_f32_16x16x32_bf16 v[102:105], v[152:155], v[230:233], v[102:105]
	v_mfma_f32_16x16x32_bf16 v[98:101], v[164:167], v[230:233], v[98:101]
	v_mfma_f32_16x16x32_bf16 v[126:129], v[160:163], v[192:195], v[126:129]
	v_mfma_f32_16x16x32_bf16 v[122:125], v[168:171], v[192:195], v[122:125]
	v_mfma_f32_16x16x32_bf16 v[118:121], v[160:163], v[218:221], v[118:121]
	v_mfma_f32_16x16x32_bf16 v[114:117], v[168:171], v[218:221], v[114:117]
	v_mfma_f32_16x16x32_bf16 v[110:113], v[160:163], v[226:229], v[110:113]
	v_mfma_f32_16x16x32_bf16 v[106:109], v[168:171], v[226:229], v[106:109]
	v_mfma_f32_16x16x32_bf16 v[102:105], v[160:163], v[234:237], v[102:105]
	v_mfma_f32_16x16x32_bf16 v[98:101], v[168:171], v[234:237], v[98:101]
	s_setprio 0
	s_setprio 1
	v_mfma_f32_16x16x32_bf16 v[60:63], v[172:175], v[188:191], v[60:63]
	v_mfma_f32_16x16x32_bf16 v[56:59], v[180:183], v[188:191], v[56:59]
	v_mfma_f32_16x16x32_bf16 v[52:55], v[172:175], v[214:217], v[52:55]
	v_mfma_f32_16x16x32_bf16 v[48:51], v[180:183], v[214:217], v[48:51]
	v_mfma_f32_16x16x32_bf16 v[44:47], v[172:175], v[222:225], v[44:47]
	v_mfma_f32_16x16x32_bf16 v[40:43], v[180:183], v[222:225], v[40:43]
	v_mfma_f32_16x16x32_bf16 v[36:39], v[172:175], v[230:233], v[36:39]
	v_mfma_f32_16x16x32_bf16 v[32:35], v[180:183], v[230:233], v[32:35]
	v_mfma_f32_16x16x32_bf16 v[60:63], v[176:179], v[192:195], v[60:63]
	v_mfma_f32_16x16x32_bf16 v[56:59], v[184:187], v[192:195], v[56:59]
	v_mfma_f32_16x16x32_bf16 v[52:55], v[176:179], v[218:221], v[52:55]
	v_mfma_f32_16x16x32_bf16 v[48:51], v[184:187], v[218:221], v[48:51]
	v_mfma_f32_16x16x32_bf16 v[44:47], v[176:179], v[226:229], v[44:47]
	v_mfma_f32_16x16x32_bf16 v[40:43], v[184:187], v[226:229], v[40:43]
	v_mfma_f32_16x16x32_bf16 v[36:39], v[176:179], v[234:237], v[36:39]
	v_mfma_f32_16x16x32_bf16 v[32:35], v[184:187], v[234:237], v[32:35]
	s_setprio 0
	s_barrier
	s_add_i32 s40, s40, s53
	v_lshl_add_u64 v[156:157], s[38:39], 0, v[132:133]
	s_mov_b32 m0, s40
	ds_read_b128 v[188:191], v143 offset:16384
	ds_read_b128 v[192:195], v143 offset:17408
	ds_read_b128 v[214:217], v143 offset:18432
	ds_read_b128 v[218:221], v143 offset:19456
	ds_read_b128 v[222:225], v143 offset:20480
	ds_read_b128 v[226:229], v143 offset:21504
	ds_read_b128 v[230:233], v143 offset:22528
	ds_read_b128 v[234:237], v143 offset:23552
	global_load_lds_dwordx4 v[156:157], off
	s_add_i32 m0, s40, 0x2000
	v_lshl_add_u64 v[238:239], s[38:39], 0, v[136:137]
	s_add_u32 s38, s38, s12
	s_addc_u32 s39, s39, s13
	s_add_i32 s37, s37, s53
	global_load_lds_dwordx4 v[238:239], off
	v_lshl_add_u64 v[240:241], s[38:39], 0, v[132:133]
	s_mov_b32 m0, s37
	v_lshl_add_u64 v[242:243], s[38:39], 0, v[136:137]
	global_load_lds_dwordx4 v[240:241], off
	s_add_i32 m0, s37, 0x2000
	v_lshl_add_u64 v[244:245], s[10:11], 0, v[130:131]
	global_load_lds_dwordx4 v[242:243], off
	s_mov_b32 m0, s54
	v_lshl_add_u64 v[246:247], s[10:11], 0, v[134:135]
	global_load_lds_dwordx4 v[244:245], off
	s_mov_b32 m0, s55
	s_nop 0
	global_load_lds_dwordx4 v[246:247], off
	s_waitcnt vmcnt(8)
	s_waitcnt lgkmcnt(0)
	s_barrier
	s_setprio 1
	s_waitcnt lgkmcnt(0)
	v_mfma_f32_16x16x32_bf16 v[94:97], v[152:155], v[188:191], v[94:97]
	v_mfma_f32_16x16x32_bf16 v[88:91], v[164:167], v[188:191], v[88:91]
	v_mfma_f32_16x16x32_bf16 v[84:87], v[152:155], v[214:217], v[84:87]
	v_mfma_f32_16x16x32_bf16 v[80:83], v[164:167], v[214:217], v[80:83]
	v_mfma_f32_16x16x32_bf16 v[76:79], v[152:155], v[222:225], v[76:79]
	v_mfma_f32_16x16x32_bf16 v[72:75], v[164:167], v[222:225], v[72:75]
	v_mfma_f32_16x16x32_bf16 v[68:71], v[152:155], v[230:233], v[68:71]
	v_mfma_f32_16x16x32_bf16 v[64:67], v[164:167], v[230:233], v[64:67]
	v_mfma_f32_16x16x32_bf16 v[94:97], v[160:163], v[192:195], v[94:97]
	v_mfma_f32_16x16x32_bf16 v[88:91], v[168:171], v[192:195], v[88:91]
	v_mfma_f32_16x16x32_bf16 v[84:87], v[160:163], v[218:221], v[84:87]
	v_mfma_f32_16x16x32_bf16 v[80:83], v[168:171], v[218:221], v[80:83]
	v_mfma_f32_16x16x32_bf16 v[76:79], v[160:163], v[226:229], v[76:79]
	v_mfma_f32_16x16x32_bf16 v[72:75], v[168:171], v[226:229], v[72:75]
	v_mfma_f32_16x16x32_bf16 v[68:71], v[160:163], v[234:237], v[68:71]
	v_mfma_f32_16x16x32_bf16 v[64:67], v[168:171], v[234:237], v[64:67]
	s_setprio 0
	s_setprio 1
	v_mfma_f32_16x16x32_bf16 v[28:31], v[172:175], v[188:191], v[28:31]
	v_mfma_f32_16x16x32_bf16 v[24:27], v[180:183], v[188:191], v[24:27]
	v_mfma_f32_16x16x32_bf16 v[20:23], v[172:175], v[214:217], v[20:23]
	v_mfma_f32_16x16x32_bf16 v[16:19], v[180:183], v[214:217], v[16:19]
	v_mfma_f32_16x16x32_bf16 v[12:15], v[172:175], v[222:225], v[12:15]
	v_mfma_f32_16x16x32_bf16 v[8:11], v[180:183], v[222:225], v[8:11]
	v_mfma_f32_16x16x32_bf16 v[4:7], v[172:175], v[230:233], v[4:7]
	v_mfma_f32_16x16x32_bf16 v[0:3], v[180:183], v[230:233], v[0:3]
	v_mfma_f32_16x16x32_bf16 v[28:31], v[176:179], v[192:195], v[28:31]
	v_mfma_f32_16x16x32_bf16 v[24:27], v[184:187], v[192:195], v[24:27]
	v_mfma_f32_16x16x32_bf16 v[20:23], v[176:179], v[218:221], v[20:23]
	v_mfma_f32_16x16x32_bf16 v[16:19], v[184:187], v[218:221], v[16:19]
	v_mfma_f32_16x16x32_bf16 v[12:15], v[176:179], v[226:229], v[12:15]
	v_mfma_f32_16x16x32_bf16 v[8:11], v[184:187], v[226:229], v[8:11]
	v_mfma_f32_16x16x32_bf16 v[4:7], v[176:179], v[234:237], v[4:7]
	v_mfma_f32_16x16x32_bf16 v[0:3], v[184:187], v[234:237], v[0:3]
	s_setprio 0
	s_barrier
	s_add_i32 s37, 0, 0x18000
	v_add_u32_e32 v92, s37, v141
	s_add_i32 s38, 0, 0x1c000
	ds_read_b128 v[152:155], v92
	ds_read_b128 v[160:163], v92 offset:1024
	ds_read_b128 v[164:167], v92 offset:2048
	ds_read_b128 v[168:171], v92 offset:3072
	v_add_u32_e32 v92, s38, v141
	ds_read_b128 v[172:175], v92
	ds_read_b128 v[176:179], v92 offset:1024
	ds_read_b128 v[180:183], v92 offset:2048
	ds_read_b128 v[184:187], v92 offset:3072
	s_add_u32 s10, s10, s16
	s_addc_u32 s11, s11, s17
	s_mov_b32 m0, s56
	v_lshl_add_u64 v[248:249], s[10:11], 0, v[130:131]
	ds_read_b128 v[188:191], v143 offset:32768
	ds_read_b128 v[192:195], v143 offset:33792
	ds_read_b128 v[214:217], v143 offset:34816
	ds_read_b128 v[218:221], v143 offset:35840
	ds_read_b128 v[222:225], v143 offset:36864
	ds_read_b128 v[226:229], v143 offset:37888
	ds_read_b128 v[230:233], v143 offset:38912
	ds_read_b128 v[234:237], v143 offset:39936
	global_load_lds_dwordx4 v[248:249], off
	v_lshl_add_u64 v[248:249], s[10:11], 0, v[134:135]
	s_mov_b32 m0, s57
	s_nop 0
	global_load_lds_dwordx4 v[248:249], off
	s_waitcnt vmcnt(8)
	s_waitcnt lgkmcnt(0)
	s_barrier
	s_setprio 1
	s_waitcnt lgkmcnt(0)
	v_mfma_f32_16x16x32_bf16 v[126:129], v[152:155], v[188:191], v[126:129]
	v_mfma_f32_16x16x32_bf16 v[122:125], v[164:167], v[188:191], v[122:125]
	v_mfma_f32_16x16x32_bf16 v[118:121], v[152:155], v[214:217], v[118:121]
	v_mfma_f32_16x16x32_bf16 v[114:117], v[164:167], v[214:217], v[114:117]
	v_mfma_f32_16x16x32_bf16 v[110:113], v[152:155], v[222:225], v[110:113]
	v_mfma_f32_16x16x32_bf16 v[106:109], v[164:167], v[222:225], v[106:109]
	v_mfma_f32_16x16x32_bf16 v[102:105], v[152:155], v[230:233], v[102:105]
	v_mfma_f32_16x16x32_bf16 v[98:101], v[164:167], v[230:233], v[98:101]
	v_mfma_f32_16x16x32_bf16 v[126:129], v[160:163], v[192:195], v[126:129]
	v_mfma_f32_16x16x32_bf16 v[122:125], v[168:171], v[192:195], v[122:125]
	v_mfma_f32_16x16x32_bf16 v[118:121], v[160:163], v[218:221], v[118:121]
	v_mfma_f32_16x16x32_bf16 v[114:117], v[168:171], v[218:221], v[114:117]
	v_mfma_f32_16x16x32_bf16 v[110:113], v[160:163], v[226:229], v[110:113]
	v_mfma_f32_16x16x32_bf16 v[106:109], v[168:171], v[226:229], v[106:109]
	v_mfma_f32_16x16x32_bf16 v[102:105], v[160:163], v[234:237], v[102:105]
	v_mfma_f32_16x16x32_bf16 v[98:101], v[168:171], v[234:237], v[98:101]
	s_setprio 0
	s_setprio 1
	v_mfma_f32_16x16x32_bf16 v[60:63], v[172:175], v[188:191], v[60:63]
	v_mfma_f32_16x16x32_bf16 v[56:59], v[180:183], v[188:191], v[56:59]
	v_mfma_f32_16x16x32_bf16 v[52:55], v[172:175], v[214:217], v[52:55]
	v_mfma_f32_16x16x32_bf16 v[48:51], v[180:183], v[214:217], v[48:51]
	v_mfma_f32_16x16x32_bf16 v[44:47], v[172:175], v[222:225], v[44:47]
	v_mfma_f32_16x16x32_bf16 v[40:43], v[180:183], v[222:225], v[40:43]
	v_mfma_f32_16x16x32_bf16 v[36:39], v[172:175], v[230:233], v[36:39]
	v_mfma_f32_16x16x32_bf16 v[32:35], v[180:183], v[230:233], v[32:35]
	v_mfma_f32_16x16x32_bf16 v[60:63], v[176:179], v[192:195], v[60:63]
	v_mfma_f32_16x16x32_bf16 v[56:59], v[184:187], v[192:195], v[56:59]
	v_mfma_f32_16x16x32_bf16 v[52:55], v[176:179], v[218:221], v[52:55]
	v_mfma_f32_16x16x32_bf16 v[48:51], v[184:187], v[218:221], v[48:51]
	v_mfma_f32_16x16x32_bf16 v[44:47], v[176:179], v[226:229], v[44:47]
	v_mfma_f32_16x16x32_bf16 v[40:43], v[184:187], v[226:229], v[40:43]
	v_mfma_f32_16x16x32_bf16 v[36:39], v[176:179], v[234:237], v[36:39]
	v_mfma_f32_16x16x32_bf16 v[32:35], v[184:187], v[234:237], v[32:35]
	s_setprio 0
	s_barrier
	s_add_i32 s10, s37, s53
	v_lshl_add_u64 v[156:157], v[156:157], 0, s[80:81]
	s_mov_b32 m0, s10
	ds_read_b128 v[188:191], v143 offset:49152
	ds_read_b128 v[192:195], v143 offset:50176
	ds_read_b128 v[214:217], v143 offset:51200
	ds_read_b128 v[218:221], v143 offset:52224
	ds_read_b128 v[222:225], v143 offset:53248
	ds_read_b128 v[226:229], v143 offset:54272
	ds_read_b128 v[230:233], v143 offset:55296
	ds_read_b128 v[234:237], v143 offset:56320
	global_load_lds_dwordx4 v[156:157], off
	v_lshl_add_u64 v[156:157], v[238:239], 0, s[80:81]
	s_add_i32 m0, s10, 0x2000
	s_add_i32 s10, s38, s53
	global_load_lds_dwordx4 v[156:157], off
	v_lshl_add_u64 v[156:157], v[240:241], 0, s[80:81]
	s_mov_b32 m0, s10
	s_nop 0
	global_load_lds_dwordx4 v[156:157], off
	v_lshl_add_u64 v[156:157], v[242:243], 0, s[80:81]
	s_add_i32 m0, s10, 0x2000
	s_nop 0
	global_load_lds_dwordx4 v[156:157], off
	v_lshl_add_u64 v[156:157], v[244:245], 0, s[80:81]
	s_mov_b32 m0, s69
	s_nop 0
	global_load_lds_dwordx4 v[156:157], off
	v_lshl_add_u64 v[156:157], v[246:247], 0, s[80:81]
	s_mov_b32 m0, s70
	s_nop 0
	global_load_lds_dwordx4 v[156:157], off
	s_waitcnt vmcnt(8)
	s_waitcnt lgkmcnt(0)
	s_barrier
	s_setprio 1
	s_waitcnt lgkmcnt(0)
	v_mfma_f32_16x16x32_bf16 v[94:97], v[152:155], v[188:191], v[94:97]
	v_mfma_f32_16x16x32_bf16 v[88:91], v[164:167], v[188:191], v[88:91]
	v_mfma_f32_16x16x32_bf16 v[84:87], v[152:155], v[214:217], v[84:87]
	v_mfma_f32_16x16x32_bf16 v[80:83], v[164:167], v[214:217], v[80:83]
	v_mfma_f32_16x16x32_bf16 v[76:79], v[152:155], v[222:225], v[76:79]
	v_mfma_f32_16x16x32_bf16 v[72:75], v[164:167], v[222:225], v[72:75]
	v_mfma_f32_16x16x32_bf16 v[68:71], v[152:155], v[230:233], v[68:71]
	v_mfma_f32_16x16x32_bf16 v[64:67], v[164:167], v[230:233], v[64:67]
	v_mfma_f32_16x16x32_bf16 v[94:97], v[160:163], v[192:195], v[94:97]
	v_mfma_f32_16x16x32_bf16 v[88:91], v[168:171], v[192:195], v[88:91]
	v_mfma_f32_16x16x32_bf16 v[84:87], v[160:163], v[218:221], v[84:87]
	v_mfma_f32_16x16x32_bf16 v[80:83], v[168:171], v[218:221], v[80:83]
	v_mfma_f32_16x16x32_bf16 v[76:79], v[160:163], v[226:229], v[76:79]
	v_mfma_f32_16x16x32_bf16 v[72:75], v[168:171], v[226:229], v[72:75]
	v_mfma_f32_16x16x32_bf16 v[68:71], v[160:163], v[234:237], v[68:71]
	v_mfma_f32_16x16x32_bf16 v[64:67], v[168:171], v[234:237], v[64:67]
	s_setprio 0
	s_setprio 1
	v_mfma_f32_16x16x32_bf16 v[28:31], v[172:175], v[188:191], v[28:31]
	v_mfma_f32_16x16x32_bf16 v[24:27], v[180:183], v[188:191], v[24:27]
	v_mfma_f32_16x16x32_bf16 v[20:23], v[172:175], v[214:217], v[20:23]
	v_mfma_f32_16x16x32_bf16 v[16:19], v[180:183], v[214:217], v[16:19]
	v_mfma_f32_16x16x32_bf16 v[12:15], v[172:175], v[222:225], v[12:15]
	v_mfma_f32_16x16x32_bf16 v[8:11], v[180:183], v[222:225], v[8:11]
	v_mfma_f32_16x16x32_bf16 v[4:7], v[172:175], v[230:233], v[4:7]
	v_mfma_f32_16x16x32_bf16 v[0:3], v[180:183], v[230:233], v[0:3]
	v_mfma_f32_16x16x32_bf16 v[28:31], v[176:179], v[192:195], v[28:31]
	v_mfma_f32_16x16x32_bf16 v[24:27], v[184:187], v[192:195], v[24:27]
	v_mfma_f32_16x16x32_bf16 v[20:23], v[176:179], v[218:221], v[20:23]
	v_mfma_f32_16x16x32_bf16 v[16:19], v[184:187], v[218:221], v[16:19]
	v_mfma_f32_16x16x32_bf16 v[12:15], v[176:179], v[226:229], v[12:15]
	v_mfma_f32_16x16x32_bf16 v[8:11], v[184:187], v[226:229], v[8:11]
	v_mfma_f32_16x16x32_bf16 v[4:7], v[176:179], v[234:237], v[4:7]
	v_mfma_f32_16x16x32_bf16 v[0:3], v[184:187], v[234:237], v[0:3]
	s_setprio 0
	s_add_u32 s8, s8, 0x100
	s_addc_u32 s9, s9, 0
	s_add_u32 s34, s34, 0x100
	s_addc_u32 s35, s35, 0
	s_cmp_ge_i32 s36, s68
	s_mov_b32 s10, s36
	s_cbranch_scc1 .Lrot7_exit
	s_add_i32 s36, s10, 2
	s_add_u32 s37, s8, 0x80
	s_addc_u32 s11, s9, 0
	s_add_i32 s40, 0, 0x10000
	s_cmp_eq_u32 s71, s10
	s_cselect_b32 s11, s29, s11
	s_cselect_b32 s10, s28, s37
	v_add_u32_e32 v92, s40, v141
	s_cselect_b32 s39, s31, s35
	s_cselect_b32 s38, s30, s34
	s_add_i32 s37, 0, 0x14000
	s_barrier
	s_branch .Lrot7_body

.Lrot6_body:
	ds_read_b128 v[80:83], v79
	ds_read_b128 v[84:87], v79 offset:1024
	ds_read_b128 v[88:91], v79 offset:2048
	ds_read_b128 v[94:97], v79 offset:3072
	s_cmp_eq_u32 s57, s24
	s_cselect_b32 s24, s6, s64
	s_cselect_b32 s25, s7, s25
	s_cselect_b32 s65, s23, s62
	s_cselect_b32 s64, s22, s61
	v_lshl_add_u64 v[130:131], s[26:27], 0, v[72:73]
	s_add_i32 m0, s45, 0xc000
	ds_read_b128 v[98:101], v78
	ds_read_b128 v[102:105], v78 offset:1024
	ds_read_b128 v[106:109], v78 offset:2048
	ds_read_b128 v[110:113], v78 offset:3072
	ds_read_b128 v[114:117], v78 offset:4096
	ds_read_b128 v[118:121], v78 offset:5120
	ds_read_b128 v[122:125], v78 offset:6144
	ds_read_b128 v[126:129], v78 offset:7168
	global_load_lds_dwordx4 v[130:131], off
	v_lshl_add_u64 v[130:131], s[26:27], 0, v[74:75]
	s_add_i32 m0, s45, 0xe000
	s_nop 0
	global_load_lds_dwordx4 v[130:131], off
	s_waitcnt vmcnt(8)
	s_waitcnt lgkmcnt(0)
	s_barrier
	s_setprio 1
	s_waitcnt lgkmcnt(0)
	v_mfma_f32_16x16x32_bf16 v[60:63], v[80:83], v[98:101], v[60:63]
	v_mfma_f32_16x16x32_bf16 v[56:59], v[88:91], v[98:101], v[56:59]
	v_mfma_f32_16x16x32_bf16 v[52:55], v[80:83], v[106:109], v[52:55]
	v_mfma_f32_16x16x32_bf16 v[48:51], v[88:91], v[106:109], v[48:51]
	v_mfma_f32_16x16x32_bf16 v[44:47], v[80:83], v[114:117], v[44:47]
	v_mfma_f32_16x16x32_bf16 v[40:43], v[88:91], v[114:117], v[40:43]
	v_mfma_f32_16x16x32_bf16 v[36:39], v[80:83], v[122:125], v[36:39]
	v_mfma_f32_16x16x32_bf16 v[32:35], v[88:91], v[122:125], v[32:35]
	v_mfma_f32_16x16x32_bf16 v[60:63], v[84:87], v[102:105], v[60:63]
	v_mfma_f32_16x16x32_bf16 v[56:59], v[94:97], v[102:105], v[56:59]
	v_mfma_f32_16x16x32_bf16 v[52:55], v[84:87], v[110:113], v[52:55]
	v_mfma_f32_16x16x32_bf16 v[48:51], v[94:97], v[110:113], v[48:51]
	v_mfma_f32_16x16x32_bf16 v[44:47], v[84:87], v[118:121], v[44:47]
	v_mfma_f32_16x16x32_bf16 v[40:43], v[94:97], v[118:121], v[40:43]
	v_mfma_f32_16x16x32_bf16 v[36:39], v[84:87], v[126:129], v[36:39]
	v_mfma_f32_16x16x32_bf16 v[32:35], v[94:97], v[126:129], v[32:35]
	s_setprio 0
	s_setprio 1
	s_setprio 0
	s_barrier
	s_add_i32 s66, s66, s40
	v_lshl_add_u64 v[130:131], s[64:65], 0, v[92:93]
	s_mov_b32 m0, s66
	ds_read_b128 v[98:101], v78 offset:16384
	ds_read_b128 v[102:105], v78 offset:17408
	ds_read_b128 v[106:109], v78 offset:18432
	ds_read_b128 v[110:113], v78 offset:19456
	ds_read_b128 v[114:117], v78 offset:20480
	ds_read_b128 v[118:121], v78 offset:21504
	ds_read_b128 v[122:125], v78 offset:22528
	ds_read_b128 v[126:129], v78 offset:23552
	global_load_lds_dwordx4 v[130:131], off
	s_add_i32 m0, s66, 0x2000
	v_lshl_add_u64 v[132:133], s[64:65], 0, v[68:69]
	s_add_u32 s64, s64, s8
	s_addc_u32 s65, s65, s9
	global_load_lds_dwordx4 v[132:133], off
	v_lshl_add_u64 v[134:135], s[64:65], 0, v[92:93]
	s_mov_b32 m0, s46
	v_lshl_add_u64 v[136:137], s[64:65], 0, v[68:69]
	global_load_lds_dwordx4 v[134:135], off
	s_mov_b32 m0, s47
	v_lshl_add_u64 v[138:139], s[24:25], 0, v[64:65]
	global_load_lds_dwordx4 v[136:137], off
	s_mov_b32 m0, s45
	v_lshl_add_u64 v[140:141], s[24:25], 0, v[66:67]
	global_load_lds_dwordx4 v[138:139], off
	s_mov_b32 m0, s48
	s_nop 0
	global_load_lds_dwordx4 v[140:141], off
	s_waitcnt vmcnt(8)
	s_waitcnt lgkmcnt(0)
	s_barrier
	s_setprio 1
	s_waitcnt lgkmcnt(0)
	v_mfma_f32_16x16x32_bf16 v[28:31], v[80:83], v[98:101], v[28:31]
	v_mfma_f32_16x16x32_bf16 v[24:27], v[88:91], v[98:101], v[24:27]
	v_mfma_f32_16x16x32_bf16 v[20:23], v[80:83], v[106:109], v[20:23]
	v_mfma_f32_16x16x32_bf16 v[16:19], v[88:91], v[106:109], v[16:19]
	v_mfma_f32_16x16x32_bf16 v[12:15], v[80:83], v[114:117], v[12:15]
	v_mfma_f32_16x16x32_bf16 v[8:11], v[88:91], v[114:117], v[8:11]
	v_mfma_f32_16x16x32_bf16 v[4:7], v[80:83], v[122:125], v[4:7]
	v_mfma_f32_16x16x32_bf16 v[0:3], v[88:91], v[122:125], v[0:3]
	v_mfma_f32_16x16x32_bf16 v[28:31], v[84:87], v[102:105], v[28:31]
	v_mfma_f32_16x16x32_bf16 v[24:27], v[94:97], v[102:105], v[24:27]
	v_mfma_f32_16x16x32_bf16 v[20:23], v[84:87], v[110:113], v[20:23]
	v_mfma_f32_16x16x32_bf16 v[16:19], v[94:97], v[110:113], v[16:19]
	v_mfma_f32_16x16x32_bf16 v[12:15], v[84:87], v[118:121], v[12:15]
	v_mfma_f32_16x16x32_bf16 v[8:11], v[94:97], v[118:121], v[8:11]
	v_mfma_f32_16x16x32_bf16 v[4:7], v[84:87], v[126:129], v[4:7]
	v_mfma_f32_16x16x32_bf16 v[0:3], v[94:97], v[126:129], v[0:3]
	s_setprio 0
	s_setprio 1
	s_setprio 0
	s_barrier
	s_add_i32 s64, 0, 0x18000
	v_add_u32_e32 v79, s64, v77
	ds_read_b128 v[80:83], v79
	ds_read_b128 v[84:87], v79 offset:1024
	ds_read_b128 v[88:91], v79 offset:2048
	ds_read_b128 v[94:97], v79 offset:3072
	s_add_u32 s24, s24, s12
	s_addc_u32 s25, s25, s13
	s_mov_b32 m0, s49
	v_lshl_add_u64 v[142:143], s[24:25], 0, v[64:65]
	ds_read_b128 v[98:101], v78 offset:32768
	ds_read_b128 v[102:105], v78 offset:33792
	ds_read_b128 v[106:109], v78 offset:34816
	ds_read_b128 v[110:113], v78 offset:35840
	ds_read_b128 v[114:117], v78 offset:36864
	ds_read_b128 v[118:121], v78 offset:37888
	ds_read_b128 v[122:125], v78 offset:38912
	ds_read_b128 v[126:129], v78 offset:39936
	global_load_lds_dwordx4 v[142:143], off
	v_lshl_add_u64 v[142:143], s[24:25], 0, v[66:67]
	s_mov_b32 m0, s50
	s_nop 0
	global_load_lds_dwordx4 v[142:143], off
	s_waitcnt vmcnt(8)
	s_waitcnt lgkmcnt(0)
	s_barrier
	s_setprio 1
	s_waitcnt lgkmcnt(0)
	v_mfma_f32_16x16x32_bf16 v[60:63], v[80:83], v[98:101], v[60:63]
	v_mfma_f32_16x16x32_bf16 v[56:59], v[88:91], v[98:101], v[56:59]
	v_mfma_f32_16x16x32_bf16 v[52:55], v[80:83], v[106:109], v[52:55]
	v_mfma_f32_16x16x32_bf16 v[48:51], v[88:91], v[106:109], v[48:51]
	v_mfma_f32_16x16x32_bf16 v[44:47], v[80:83], v[114:117], v[44:47]
	v_mfma_f32_16x16x32_bf16 v[40:43], v[88:91], v[114:117], v[40:43]
	v_mfma_f32_16x16x32_bf16 v[36:39], v[80:83], v[122:125], v[36:39]
	v_mfma_f32_16x16x32_bf16 v[32:35], v[88:91], v[122:125], v[32:35]
	v_mfma_f32_16x16x32_bf16 v[60:63], v[84:87], v[102:105], v[60:63]
	v_mfma_f32_16x16x32_bf16 v[56:59], v[94:97], v[102:105], v[56:59]
	v_mfma_f32_16x16x32_bf16 v[52:55], v[84:87], v[110:113], v[52:55]
	v_mfma_f32_16x16x32_bf16 v[48:51], v[94:97], v[110:113], v[48:51]
	v_mfma_f32_16x16x32_bf16 v[44:47], v[84:87], v[118:121], v[44:47]
	v_mfma_f32_16x16x32_bf16 v[40:43], v[94:97], v[118:121], v[40:43]
	v_mfma_f32_16x16x32_bf16 v[36:39], v[84:87], v[126:129], v[36:39]
	v_mfma_f32_16x16x32_bf16 v[32:35], v[94:97], v[126:129], v[32:35]
	s_setprio 0
	s_setprio 1
	s_setprio 0
	s_barrier
	s_add_i32 s24, s64, s40
	v_lshl_add_u64 v[130:131], v[130:131], 0, s[80:81]
	s_mov_b32 m0, s24
	ds_read_b128 v[98:101], v78 offset:49152
	ds_read_b128 v[102:105], v78 offset:50176
	ds_read_b128 v[106:109], v78 offset:51200
	ds_read_b128 v[110:113], v78 offset:52224
	ds_read_b128 v[114:117], v78 offset:53248
	ds_read_b128 v[118:121], v78 offset:54272
	ds_read_b128 v[122:125], v78 offset:55296
	ds_read_b128 v[126:129], v78 offset:56320
	global_load_lds_dwordx4 v[130:131], off
	v_lshl_add_u64 v[130:131], v[132:133], 0, s[80:81]
	s_add_i32 m0, s24, 0x2000
	s_nop 0
	global_load_lds_dwordx4 v[130:131], off
	v_lshl_add_u64 v[130:131], v[134:135], 0, s[80:81]
	s_mov_b32 m0, s55
	s_nop 0
	global_load_lds_dwordx4 v[130:131], off
	v_lshl_add_u64 v[130:131], v[136:137], 0, s[80:81]
	s_mov_b32 m0, s56
	s_nop 0
	global_load_lds_dwordx4 v[130:131], off
	v_lshl_add_u64 v[130:131], v[138:139], 0, s[80:81]
	s_mov_b32 m0, s53
	s_nop 0
	global_load_lds_dwordx4 v[130:131], off
	v_lshl_add_u64 v[130:131], v[140:141], 0, s[80:81]
	s_mov_b32 m0, s54
	s_nop 0
	global_load_lds_dwordx4 v[130:131], off
	s_waitcnt vmcnt(8)
	s_waitcnt lgkmcnt(0)
	s_barrier
	s_setprio 1
	s_waitcnt lgkmcnt(0)
	v_mfma_f32_16x16x32_bf16 v[28:31], v[80:83], v[98:101], v[28:31]
	v_mfma_f32_16x16x32_bf16 v[24:27], v[88:91], v[98:101], v[24:27]
	v_mfma_f32_16x16x32_bf16 v[20:23], v[80:83], v[106:109], v[20:23]
	v_mfma_f32_16x16x32_bf16 v[16:19], v[88:91], v[106:109], v[16:19]
	v_mfma_f32_16x16x32_bf16 v[12:15], v[80:83], v[114:117], v[12:15]
	v_mfma_f32_16x16x32_bf16 v[8:11], v[88:91], v[114:117], v[8:11]
	v_mfma_f32_16x16x32_bf16 v[4:7], v[80:83], v[122:125], v[4:7]
	v_mfma_f32_16x16x32_bf16 v[0:3], v[88:91], v[122:125], v[0:3]
	v_mfma_f32_16x16x32_bf16 v[28:31], v[84:87], v[102:105], v[28:31]
	v_mfma_f32_16x16x32_bf16 v[24:27], v[94:97], v[102:105], v[24:27]
	v_mfma_f32_16x16x32_bf16 v[20:23], v[84:87], v[110:113], v[20:23]
	v_mfma_f32_16x16x32_bf16 v[16:19], v[94:97], v[110:113], v[16:19]
	v_mfma_f32_16x16x32_bf16 v[12:15], v[84:87], v[118:121], v[12:15]
	v_mfma_f32_16x16x32_bf16 v[8:11], v[94:97], v[118:121], v[8:11]
	v_mfma_f32_16x16x32_bf16 v[4:7], v[84:87], v[126:129], v[4:7]
	v_mfma_f32_16x16x32_bf16 v[0:3], v[94:97], v[126:129], v[0:3]
	s_setprio 0
	s_setprio 1
	s_setprio 0
	s_add_u32 s26, s26, 0x100
	s_addc_u32 s27, s27, 0
	s_add_u32 s61, s61, 0x100
	s_addc_u32 s62, s62, 0
	s_cmp_ge_i32 s63, s51
	s_mov_b32 s24, s63
	s_cbranch_scc1 .Lrot6_exit
	s_add_i32 s63, s24, 2
	s_add_u32 s64, s26, 0x80
	s_addc_u32 s25, s27, 0
	s_add_i32 s66, 0, 0x10000
	v_add_u32_e32 v79, s66, v77
	s_barrier
	s_branch .Lrot6_body

.Lrot5_body:
	ds_read_b128 v[130:133], v142
	ds_read_b128 v[134:137], v142 offset:1024
	ds_read_b128 v[138:141], v142 offset:2048
	ds_read_b128 v[142:145], v142 offset:3072
	ds_read_b128 v[160:163], v156
	ds_read_b128 v[168:171], v156 offset:1024
	ds_read_b128 v[172:175], v156 offset:2048
	ds_read_b128 v[176:179], v156 offset:3072
	v_lshl_add_u64 v[156:157], s[28:29], 0, v[152:153]
	s_add_i32 m0, s46, 0xc000
	ds_read_b128 v[180:183], v166
	ds_read_b128 v[184:187], v166 offset:1024
	ds_read_b128 v[188:191], v166 offset:2048
	ds_read_b128 v[192:195], v166 offset:3072
	ds_read_b128 v[214:217], v166 offset:4096
	ds_read_b128 v[218:221], v166 offset:5120
	ds_read_b128 v[222:225], v166 offset:6144
	ds_read_b128 v[226:229], v166 offset:7168
	global_load_lds_dwordx4 v[156:157], off
	v_lshl_add_u64 v[156:157], s[28:29], 0, v[154:155]
	s_add_i32 m0, s46, 0xe000
	s_nop 0
	global_load_lds_dwordx4 v[156:157], off
	s_waitcnt vmcnt(8)
	s_waitcnt lgkmcnt(0)
	s_barrier
	s_setprio 1
	s_waitcnt lgkmcnt(0)
	v_mfma_f32_16x16x32_bf16 v[126:129], v[130:133], v[180:183], v[126:129]
	v_mfma_f32_16x16x32_bf16 v[122:125], v[138:141], v[180:183], v[122:125]
	v_mfma_f32_16x16x32_bf16 v[110:113], v[130:133], v[188:191], v[110:113]
	v_mfma_f32_16x16x32_bf16 v[106:109], v[138:141], v[188:191], v[106:109]
	v_mfma_f32_16x16x32_bf16 v[94:97], v[130:133], v[214:217], v[94:97]
	v_mfma_f32_16x16x32_bf16 v[88:91], v[138:141], v[214:217], v[88:91]
	v_mfma_f32_16x16x32_bf16 v[76:79], v[130:133], v[222:225], v[76:79]
	v_mfma_f32_16x16x32_bf16 v[72:75], v[138:141], v[222:225], v[72:75]
	v_mfma_f32_16x16x32_bf16 v[126:129], v[134:137], v[184:187], v[126:129]
	v_mfma_f32_16x16x32_bf16 v[122:125], v[142:145], v[184:187], v[122:125]
	v_mfma_f32_16x16x32_bf16 v[110:113], v[134:137], v[192:195], v[110:113]
	v_mfma_f32_16x16x32_bf16 v[106:109], v[142:145], v[192:195], v[106:109]
	v_mfma_f32_16x16x32_bf16 v[94:97], v[134:137], v[218:221], v[94:97]
	v_mfma_f32_16x16x32_bf16 v[88:91], v[142:145], v[218:221], v[88:91]
	v_mfma_f32_16x16x32_bf16 v[76:79], v[134:137], v[226:229], v[76:79]
	v_mfma_f32_16x16x32_bf16 v[72:75], v[142:145], v[226:229], v[72:75]
	s_setprio 0
	s_setprio 1
	v_mfma_f32_16x16x32_bf16 v[118:121], v[160:163], v[180:183], v[118:121]
	v_mfma_f32_16x16x32_bf16 v[114:117], v[172:175], v[180:183], v[114:117]
	v_mfma_f32_16x16x32_bf16 v[102:105], v[160:163], v[188:191], v[102:105]
	v_mfma_f32_16x16x32_bf16 v[98:101], v[172:175], v[188:191], v[98:101]
	v_mfma_f32_16x16x32_bf16 v[84:87], v[160:163], v[214:217], v[84:87]
	v_mfma_f32_16x16x32_bf16 v[80:83], v[172:175], v[214:217], v[80:83]
	v_mfma_f32_16x16x32_bf16 v[68:71], v[160:163], v[222:225], v[68:71]
	v_mfma_f32_16x16x32_bf16 v[64:67], v[172:175], v[222:225], v[64:67]
	v_mfma_f32_16x16x32_bf16 v[118:121], v[168:171], v[184:187], v[118:121]
	v_mfma_f32_16x16x32_bf16 v[114:117], v[176:179], v[184:187], v[114:117]
	v_mfma_f32_16x16x32_bf16 v[102:105], v[168:171], v[192:195], v[102:105]
	v_mfma_f32_16x16x32_bf16 v[98:101], v[176:179], v[192:195], v[98:101]
	v_mfma_f32_16x16x32_bf16 v[84:87], v[168:171], v[218:221], v[84:87]
	v_mfma_f32_16x16x32_bf16 v[80:83], v[176:179], v[218:221], v[80:83]
	v_mfma_f32_16x16x32_bf16 v[68:71], v[168:171], v[226:229], v[68:71]
	v_mfma_f32_16x16x32_bf16 v[64:67], v[176:179], v[226:229], v[64:67]
	s_setprio 0
	s_barrier
	s_add_i32 s66, s66, s41
	v_lshl_add_u64 v[156:157], s[64:65], 0, v[92:93]
	s_mov_b32 m0, s66
	ds_read_b128 v[180:183], v166 offset:16384
	ds_read_b128 v[184:187], v166 offset:17408
	ds_read_b128 v[188:191], v166 offset:18432
	ds_read_b128 v[192:195], v166 offset:19456
	ds_read_b128 v[214:217], v166 offset:20480
	ds_read_b128 v[218:221], v166 offset:21504
	ds_read_b128 v[222:225], v166 offset:22528
	ds_read_b128 v[226:229], v166 offset:23552
	global_load_lds_dwordx4 v[156:157], off
	s_add_i32 m0, s66, 0x2000
	v_lshl_add_u64 v[230:231], s[64:65], 0, v[150:151]
	s_add_u32 s64, s64, s8
	s_addc_u32 s65, s65, s9
	s_add_i32 s66, s67, s41
	global_load_lds_dwordx4 v[230:231], off
	v_lshl_add_u64 v[232:233], s[64:65], 0, v[92:93]
	s_mov_b32 m0, s66
	v_lshl_add_u64 v[234:235], s[64:65], 0, v[150:151]
	global_load_lds_dwordx4 v[232:233], off
	s_add_i32 m0, s66, 0x2000
	v_lshl_add_u64 v[236:237], s[30:31], 0, v[146:147]
	global_load_lds_dwordx4 v[234:235], off
	s_mov_b32 m0, s46
	v_lshl_add_u64 v[238:239], s[30:31], 0, v[148:149]
	global_load_lds_dwordx4 v[236:237], off
	s_mov_b32 m0, s47
	s_nop 0
	global_load_lds_dwordx4 v[238:239], off
	s_waitcnt vmcnt(8)
	s_waitcnt lgkmcnt(0)
	s_barrier
	s_setprio 1
	s_waitcnt lgkmcnt(0)
	v_mfma_f32_16x16x32_bf16 v[60:63], v[130:133], v[180:183], v[60:63]
	v_mfma_f32_16x16x32_bf16 v[56:59], v[138:141], v[180:183], v[56:59]
	v_mfma_f32_16x16x32_bf16 v[44:47], v[130:133], v[188:191], v[44:47]
	v_mfma_f32_16x16x32_bf16 v[40:43], v[138:141], v[188:191], v[40:43]
	v_mfma_f32_16x16x32_bf16 v[28:31], v[130:133], v[214:217], v[28:31]
	v_mfma_f32_16x16x32_bf16 v[24:27], v[138:141], v[214:217], v[24:27]
	v_mfma_f32_16x16x32_bf16 v[12:15], v[130:133], v[222:225], v[12:15]
	v_mfma_f32_16x16x32_bf16 v[8:11], v[138:141], v[222:225], v[8:11]
	v_mfma_f32_16x16x32_bf16 v[60:63], v[134:137], v[184:187], v[60:63]
	v_mfma_f32_16x16x32_bf16 v[56:59], v[142:145], v[184:187], v[56:59]
	v_mfma_f32_16x16x32_bf16 v[44:47], v[134:137], v[192:195], v[44:47]
	v_mfma_f32_16x16x32_bf16 v[40:43], v[142:145], v[192:195], v[40:43]
	v_mfma_f32_16x16x32_bf16 v[28:31], v[134:137], v[218:221], v[28:31]
	v_mfma_f32_16x16x32_bf16 v[24:27], v[142:145], v[218:221], v[24:27]
	v_mfma_f32_16x16x32_bf16 v[12:15], v[134:137], v[226:229], v[12:15]
	v_mfma_f32_16x16x32_bf16 v[8:11], v[142:145], v[226:229], v[8:11]
	s_setprio 0
	s_setprio 1
	v_mfma_f32_16x16x32_bf16 v[52:55], v[160:163], v[180:183], v[52:55]
	v_mfma_f32_16x16x32_bf16 v[48:51], v[172:175], v[180:183], v[48:51]
	v_mfma_f32_16x16x32_bf16 v[36:39], v[160:163], v[188:191], v[36:39]
	v_mfma_f32_16x16x32_bf16 v[32:35], v[172:175], v[188:191], v[32:35]
	v_mfma_f32_16x16x32_bf16 v[20:23], v[160:163], v[214:217], v[20:23]
	v_mfma_f32_16x16x32_bf16 v[16:19], v[172:175], v[214:217], v[16:19]
	v_mfma_f32_16x16x32_bf16 v[4:7], v[160:163], v[222:225], v[4:7]
	v_mfma_f32_16x16x32_bf16 v[0:3], v[172:175], v[222:225], v[0:3]
	v_mfma_f32_16x16x32_bf16 v[52:55], v[168:171], v[184:187], v[52:55]
	v_mfma_f32_16x16x32_bf16 v[48:51], v[176:179], v[184:187], v[48:51]
	v_mfma_f32_16x16x32_bf16 v[36:39], v[168:171], v[192:195], v[36:39]
	v_mfma_f32_16x16x32_bf16 v[32:35], v[176:179], v[192:195], v[32:35]
	v_mfma_f32_16x16x32_bf16 v[20:23], v[168:171], v[218:221], v[20:23]
	v_mfma_f32_16x16x32_bf16 v[16:19], v[176:179], v[218:221], v[16:19]
	v_mfma_f32_16x16x32_bf16 v[4:7], v[168:171], v[226:229], v[4:7]
	v_mfma_f32_16x16x32_bf16 v[0:3], v[176:179], v[226:229], v[0:3]
	s_setprio 0
	s_barrier
	s_add_i32 s64, 0, 0x18000
	s_add_i32 s65, 0, 0x1c000
	v_add_u32_e32 v142, s64, v164
	v_add_u32_e32 v167, s65, v164
	ds_read_b128 v[130:133], v142
	ds_read_b128 v[134:137], v142 offset:1024
	ds_read_b128 v[138:141], v142 offset:2048
	ds_read_b128 v[142:145], v142 offset:3072
	ds_read_b128 v[160:163], v167
	ds_read_b128 v[168:171], v167 offset:1024
	ds_read_b128 v[172:175], v167 offset:2048
	ds_read_b128 v[176:179], v167 offset:3072
	s_add_u32 s30, s30, s12
	s_addc_u32 s31, s31, s13
	s_mov_b32 m0, s48
	v_lshl_add_u64 v[240:241], s[30:31], 0, v[146:147]
	ds_read_b128 v[180:183], v166 offset:32768
	ds_read_b128 v[184:187], v166 offset:33792
	ds_read_b128 v[188:191], v166 offset:34816
	ds_read_b128 v[192:195], v166 offset:35840
	ds_read_b128 v[214:217], v166 offset:36864
	ds_read_b128 v[218:221], v166 offset:37888
	ds_read_b128 v[222:225], v166 offset:38912
	ds_read_b128 v[226:229], v166 offset:39936
	global_load_lds_dwordx4 v[240:241], off
	v_lshl_add_u64 v[240:241], s[30:31], 0, v[148:149]
	s_mov_b32 m0, s49
	s_nop 0
	global_load_lds_dwordx4 v[240:241], off
	s_waitcnt vmcnt(8)
	s_waitcnt lgkmcnt(0)
	s_barrier
	s_setprio 1
	s_waitcnt lgkmcnt(0)
	v_mfma_f32_16x16x32_bf16 v[126:129], v[130:133], v[180:183], v[126:129]
	v_mfma_f32_16x16x32_bf16 v[122:125], v[138:141], v[180:183], v[122:125]
	v_mfma_f32_16x16x32_bf16 v[110:113], v[130:133], v[188:191], v[110:113]
	v_mfma_f32_16x16x32_bf16 v[106:109], v[138:141], v[188:191], v[106:109]
	v_mfma_f32_16x16x32_bf16 v[94:97], v[130:133], v[214:217], v[94:97]
	v_mfma_f32_16x16x32_bf16 v[88:91], v[138:141], v[214:217], v[88:91]
	v_mfma_f32_16x16x32_bf16 v[76:79], v[130:133], v[222:225], v[76:79]
	v_mfma_f32_16x16x32_bf16 v[72:75], v[138:141], v[222:225], v[72:75]
	v_mfma_f32_16x16x32_bf16 v[126:129], v[134:137], v[184:187], v[126:129]
	v_mfma_f32_16x16x32_bf16 v[122:125], v[142:145], v[184:187], v[122:125]
	v_mfma_f32_16x16x32_bf16 v[110:113], v[134:137], v[192:195], v[110:113]
	v_mfma_f32_16x16x32_bf16 v[106:109], v[142:145], v[192:195], v[106:109]
	v_mfma_f32_16x16x32_bf16 v[94:97], v[134:137], v[218:221], v[94:97]
	v_mfma_f32_16x16x32_bf16 v[88:91], v[142:145], v[218:221], v[88:91]
	v_mfma_f32_16x16x32_bf16 v[76:79], v[134:137], v[226:229], v[76:79]
	v_mfma_f32_16x16x32_bf16 v[72:75], v[142:145], v[226:229], v[72:75]
	s_setprio 0
	s_setprio 1
	v_mfma_f32_16x16x32_bf16 v[118:121], v[160:163], v[180:183], v[118:121]
	v_mfma_f32_16x16x32_bf16 v[114:117], v[172:175], v[180:183], v[114:117]
	v_mfma_f32_16x16x32_bf16 v[102:105], v[160:163], v[188:191], v[102:105]
	v_mfma_f32_16x16x32_bf16 v[98:101], v[172:175], v[188:191], v[98:101]
	v_mfma_f32_16x16x32_bf16 v[84:87], v[160:163], v[214:217], v[84:87]
	v_mfma_f32_16x16x32_bf16 v[80:83], v[172:175], v[214:217], v[80:83]
	v_mfma_f32_16x16x32_bf16 v[68:71], v[160:163], v[222:225], v[68:71]
	v_mfma_f32_16x16x32_bf16 v[64:67], v[172:175], v[222:225], v[64:67]
	v_mfma_f32_16x16x32_bf16 v[118:121], v[168:171], v[184:187], v[118:121]
	v_mfma_f32_16x16x32_bf16 v[114:117], v[176:179], v[184:187], v[114:117]
	v_mfma_f32_16x16x32_bf16 v[102:105], v[168:171], v[192:195], v[102:105]
	v_mfma_f32_16x16x32_bf16 v[98:101], v[176:179], v[192:195], v[98:101]
	v_mfma_f32_16x16x32_bf16 v[84:87], v[168:171], v[218:221], v[84:87]
	v_mfma_f32_16x16x32_bf16 v[80:83], v[176:179], v[218:221], v[80:83]
	v_mfma_f32_16x16x32_bf16 v[68:71], v[168:171], v[226:229], v[68:71]
	v_mfma_f32_16x16x32_bf16 v[64:67], v[176:179], v[226:229], v[64:67]
	s_setprio 0
	s_barrier
	s_add_i32 s30, s64, s41
	v_lshl_add_u64 v[156:157], v[156:157], 0, s[80:81]
	s_mov_b32 m0, s30
	ds_read_b128 v[180:183], v166 offset:49152
	ds_read_b128 v[184:187], v166 offset:50176
	ds_read_b128 v[188:191], v166 offset:51200
	ds_read_b128 v[192:195], v166 offset:52224
	ds_read_b128 v[214:217], v166 offset:53248
	ds_read_b128 v[218:221], v166 offset:54272
	ds_read_b128 v[222:225], v166 offset:55296
	ds_read_b128 v[226:229], v166 offset:56320
	global_load_lds_dwordx4 v[156:157], off
	v_lshl_add_u64 v[156:157], v[230:231], 0, s[80:81]
	s_add_i32 m0, s30, 0x2000
	s_add_i32 s30, s65, s41
	global_load_lds_dwordx4 v[156:157], off
	v_lshl_add_u64 v[156:157], v[232:233], 0, s[80:81]
	s_mov_b32 m0, s30
	s_nop 0
	global_load_lds_dwordx4 v[156:157], off
	v_lshl_add_u64 v[156:157], v[234:235], 0, s[80:81]
	s_add_i32 m0, s30, 0x2000
	s_nop 0
	global_load_lds_dwordx4 v[156:157], off
	v_lshl_add_u64 v[156:157], v[236:237], 0, s[80:81]
	s_mov_b32 m0, s53
	s_nop 0
	global_load_lds_dwordx4 v[156:157], off
	v_lshl_add_u64 v[156:157], v[238:239], 0, s[80:81]
	s_mov_b32 m0, s54
	s_nop 0
	global_load_lds_dwordx4 v[156:157], off
	s_waitcnt vmcnt(8)
	s_waitcnt lgkmcnt(0)
	s_barrier
	s_setprio 1
	s_waitcnt lgkmcnt(0)
	v_mfma_f32_16x16x32_bf16 v[60:63], v[130:133], v[180:183], v[60:63]
	v_mfma_f32_16x16x32_bf16 v[56:59], v[138:141], v[180:183], v[56:59]
	v_mfma_f32_16x16x32_bf16 v[44:47], v[130:133], v[188:191], v[44:47]
	v_mfma_f32_16x16x32_bf16 v[40:43], v[138:141], v[188:191], v[40:43]
	v_mfma_f32_16x16x32_bf16 v[28:31], v[130:133], v[214:217], v[28:31]
	v_mfma_f32_16x16x32_bf16 v[24:27], v[138:141], v[214:217], v[24:27]
	v_mfma_f32_16x16x32_bf16 v[12:15], v[130:133], v[222:225], v[12:15]
	v_mfma_f32_16x16x32_bf16 v[8:11], v[138:141], v[222:225], v[8:11]
	v_mfma_f32_16x16x32_bf16 v[60:63], v[134:137], v[184:187], v[60:63]
	v_mfma_f32_16x16x32_bf16 v[56:59], v[142:145], v[184:187], v[56:59]
	v_mfma_f32_16x16x32_bf16 v[44:47], v[134:137], v[192:195], v[44:47]
	v_mfma_f32_16x16x32_bf16 v[40:43], v[142:145], v[192:195], v[40:43]
	v_mfma_f32_16x16x32_bf16 v[28:31], v[134:137], v[218:221], v[28:31]
	v_mfma_f32_16x16x32_bf16 v[24:27], v[142:145], v[218:221], v[24:27]
	v_mfma_f32_16x16x32_bf16 v[12:15], v[134:137], v[226:229], v[12:15]
	v_mfma_f32_16x16x32_bf16 v[8:11], v[142:145], v[226:229], v[8:11]
	s_setprio 0
	s_setprio 1
	v_mfma_f32_16x16x32_bf16 v[52:55], v[160:163], v[180:183], v[52:55]
	v_mfma_f32_16x16x32_bf16 v[48:51], v[172:175], v[180:183], v[48:51]
	v_mfma_f32_16x16x32_bf16 v[36:39], v[160:163], v[188:191], v[36:39]
	v_mfma_f32_16x16x32_bf16 v[32:35], v[172:175], v[188:191], v[32:35]
	v_mfma_f32_16x16x32_bf16 v[20:23], v[160:163], v[214:217], v[20:23]
	v_mfma_f32_16x16x32_bf16 v[16:19], v[172:175], v[214:217], v[16:19]
	v_mfma_f32_16x16x32_bf16 v[4:7], v[160:163], v[222:225], v[4:7]
	v_mfma_f32_16x16x32_bf16 v[0:3], v[172:175], v[222:225], v[0:3]
	v_mfma_f32_16x16x32_bf16 v[52:55], v[168:171], v[184:187], v[52:55]
	v_mfma_f32_16x16x32_bf16 v[48:51], v[176:179], v[184:187], v[48:51]
	v_mfma_f32_16x16x32_bf16 v[36:39], v[168:171], v[192:195], v[36:39]
	v_mfma_f32_16x16x32_bf16 v[32:35], v[176:179], v[192:195], v[32:35]
	v_mfma_f32_16x16x32_bf16 v[20:23], v[168:171], v[218:221], v[20:23]
	v_mfma_f32_16x16x32_bf16 v[16:19], v[176:179], v[218:221], v[16:19]
	v_mfma_f32_16x16x32_bf16 v[4:7], v[168:171], v[226:229], v[4:7]
	v_mfma_f32_16x16x32_bf16 v[0:3], v[176:179], v[226:229], v[0:3]
	s_setprio 0
	s_add_u32 s28, s28, 0x100
	s_addc_u32 s29, s29, 0
	s_add_u32 s61, s61, 0x100
	s_addc_u32 s62, s62, 0
	s_cmp_ge_i32 s63, s52
	s_mov_b32 s30, s63
	s_cbranch_scc1 .Lrot5_exit
	s_add_i32 s63, s30, 2
	s_add_u32 s64, s28, 0x80
	s_addc_u32 s31, s29, 0
	s_add_i32 s66, 0, 0x10000
	s_cmp_eq_u32 s55, s30
	s_cselect_b32 s31, s7, s31
	s_cselect_b32 s30, s6, s64
	s_cselect_b32 s65, s27, s62
	s_cselect_b32 s64, s26, s61
	s_add_i32 s67, 0, 0x14000
	v_add_u32_e32 v142, s66, v164
	v_add_u32_e32 v156, s67, v164
	s_barrier
	s_branch .Lrot5_body

.Lrot4_body:
	ds_read_b128 v[144:147], v156
	ds_read_b128 v[148:151], v156 offset:1024
	ds_read_b128 v[152:155], v156 offset:2048
	ds_read_b128 v[160:163], v156 offset:3072
	v_add_u32_e32 v156, s63, v141
	ds_read_b128 v[164:167], v156
	ds_read_b128 v[168:171], v156 offset:1024
	ds_read_b128 v[172:175], v156 offset:2048
	ds_read_b128 v[176:179], v156 offset:3072
	v_lshl_add_u64 v[156:157], s[26:27], 0, v[136:137]
	s_add_i32 m0, s44, 0xc000
	ds_read_b128 v[180:183], v143
	ds_read_b128 v[184:187], v143 offset:1024
	ds_read_b128 v[188:191], v143 offset:2048
	ds_read_b128 v[192:195], v143 offset:3072
	ds_read_b128 v[214:217], v143 offset:4096
	ds_read_b128 v[218:221], v143 offset:5120
	ds_read_b128 v[222:225], v143 offset:6144
	ds_read_b128 v[226:229], v143 offset:7168
	global_load_lds_dwordx4 v[156:157], off
	v_lshl_add_u64 v[156:157], s[26:27], 0, v[138:139]
	s_add_i32 m0, s44, 0xe000
	s_nop 0
	global_load_lds_dwordx4 v[156:157], off
	s_waitcnt vmcnt(8)
	s_waitcnt lgkmcnt(0)
	s_barrier
	s_setprio 1
	s_waitcnt lgkmcnt(0)
	v_mfma_f32_16x16x32_bf16 v[122:125], v[144:147], v[180:183], v[122:125]
	v_mfma_f32_16x16x32_bf16 v[126:129], v[152:155], v[180:183], v[126:129]
	v_mfma_f32_16x16x32_bf16 v[110:113], v[144:147], v[188:191], v[110:113]
	v_mfma_f32_16x16x32_bf16 v[106:109], v[152:155], v[188:191], v[106:109]
	v_mfma_f32_16x16x32_bf16 v[94:97], v[144:147], v[214:217], v[94:97]
	v_mfma_f32_16x16x32_bf16 v[88:91], v[152:155], v[214:217], v[88:91]
	v_mfma_f32_16x16x32_bf16 v[76:79], v[144:147], v[222:225], v[76:79]
	v_mfma_f32_16x16x32_bf16 v[72:75], v[152:155], v[222:225], v[72:75]
	v_mfma_f32_16x16x32_bf16 v[122:125], v[148:151], v[184:187], v[122:125]
	v_mfma_f32_16x16x32_bf16 v[126:129], v[160:163], v[184:187], v[126:129]
	v_mfma_f32_16x16x32_bf16 v[110:113], v[148:151], v[192:195], v[110:113]
	v_mfma_f32_16x16x32_bf16 v[106:109], v[160:163], v[192:195], v[106:109]
	v_mfma_f32_16x16x32_bf16 v[94:97], v[148:151], v[218:221], v[94:97]
	v_mfma_f32_16x16x32_bf16 v[88:91], v[160:163], v[218:221], v[88:91]
	v_mfma_f32_16x16x32_bf16 v[76:79], v[148:151], v[226:229], v[76:79]
	v_mfma_f32_16x16x32_bf16 v[72:75], v[160:163], v[226:229], v[72:75]
	s_setprio 0
	s_setprio 1
	v_mfma_f32_16x16x32_bf16 v[118:121], v[164:167], v[180:183], v[118:121]
	v_mfma_f32_16x16x32_bf16 v[114:117], v[172:175], v[180:183], v[114:117]
	v_mfma_f32_16x16x32_bf16 v[102:105], v[164:167], v[188:191], v[102:105]
	v_mfma_f32_16x16x32_bf16 v[98:101], v[172:175], v[188:191], v[98:101]
	v_mfma_f32_16x16x32_bf16 v[84:87], v[164:167], v[214:217], v[84:87]
	v_mfma_f32_16x16x32_bf16 v[80:83], v[172:175], v[214:217], v[80:83]
	v_mfma_f32_16x16x32_bf16 v[68:71], v[164:167], v[222:225], v[68:71]
	v_mfma_f32_16x16x32_bf16 v[64:67], v[172:175], v[222:225], v[64:67]
	v_mfma_f32_16x16x32_bf16 v[118:121], v[168:171], v[184:187], v[118:121]
	v_mfma_f32_16x16x32_bf16 v[114:117], v[176:179], v[184:187], v[114:117]
	v_mfma_f32_16x16x32_bf16 v[102:105], v[168:171], v[192:195], v[102:105]
	v_mfma_f32_16x16x32_bf16 v[98:101], v[176:179], v[192:195], v[98:101]
	v_mfma_f32_16x16x32_bf16 v[84:87], v[168:171], v[218:221], v[84:87]
	v_mfma_f32_16x16x32_bf16 v[80:83], v[176:179], v[218:221], v[80:83]
	v_mfma_f32_16x16x32_bf16 v[68:71], v[168:171], v[226:229], v[68:71]
	v_mfma_f32_16x16x32_bf16 v[64:67], v[176:179], v[226:229], v[64:67]
	s_setprio 0
	s_barrier
	s_add_i32 s62, s62, s39
	v_lshl_add_u64 v[156:157], s[60:61], 0, v[92:93]
	s_mov_b32 m0, s62
	ds_read_b128 v[180:183], v143 offset:16384
	ds_read_b128 v[184:187], v143 offset:17408
	ds_read_b128 v[188:191], v143 offset:18432
	ds_read_b128 v[192:195], v143 offset:19456
	ds_read_b128 v[214:217], v143 offset:20480
	ds_read_b128 v[218:221], v143 offset:21504
	ds_read_b128 v[222:225], v143 offset:22528
	ds_read_b128 v[226:229], v143 offset:23552
	global_load_lds_dwordx4 v[156:157], off
	s_add_i32 m0, s62, 0x2000
	v_lshl_add_u64 v[230:231], s[60:61], 0, v[134:135]
	s_add_u32 s60, s60, s8
	s_addc_u32 s61, s61, s9
	s_add_i32 s62, s63, s39
	global_load_lds_dwordx4 v[230:231], off
	v_lshl_add_u64 v[232:233], s[60:61], 0, v[92:93]
	s_mov_b32 m0, s62
	v_lshl_add_u64 v[234:235], s[60:61], 0, v[134:135]
	global_load_lds_dwordx4 v[232:233], off
	s_add_i32 m0, s62, 0x2000
	v_lshl_add_u64 v[236:237], s[28:29], 0, v[130:131]
	global_load_lds_dwordx4 v[234:235], off
	s_mov_b32 m0, s44
	v_lshl_add_u64 v[238:239], s[28:29], 0, v[132:133]
	global_load_lds_dwordx4 v[236:237], off
	s_mov_b32 m0, s45
	s_nop 0
	global_load_lds_dwordx4 v[238:239], off
	s_waitcnt vmcnt(8)
	s_waitcnt lgkmcnt(0)
	s_barrier
	s_setprio 1
	s_waitcnt lgkmcnt(0)
	v_mfma_f32_16x16x32_bf16 v[60:63], v[144:147], v[180:183], v[60:63]
	v_mfma_f32_16x16x32_bf16 v[56:59], v[152:155], v[180:183], v[56:59]
	v_mfma_f32_16x16x32_bf16 v[44:47], v[144:147], v[188:191], v[44:47]
	v_mfma_f32_16x16x32_bf16 v[40:43], v[152:155], v[188:191], v[40:43]
	v_mfma_f32_16x16x32_bf16 v[28:31], v[144:147], v[214:217], v[28:31]
	v_mfma_f32_16x16x32_bf16 v[24:27], v[152:155], v[214:217], v[24:27]
	v_mfma_f32_16x16x32_bf16 v[12:15], v[144:147], v[222:225], v[12:15]
	v_mfma_f32_16x16x32_bf16 v[8:11], v[152:155], v[222:225], v[8:11]
	v_mfma_f32_16x16x32_bf16 v[60:63], v[148:151], v[184:187], v[60:63]
	v_mfma_f32_16x16x32_bf16 v[56:59], v[160:163], v[184:187], v[56:59]
	v_mfma_f32_16x16x32_bf16 v[44:47], v[148:151], v[192:195], v[44:47]
	v_mfma_f32_16x16x32_bf16 v[40:43], v[160:163], v[192:195], v[40:43]
	v_mfma_f32_16x16x32_bf16 v[28:31], v[148:151], v[218:221], v[28:31]
	v_mfma_f32_16x16x32_bf16 v[24:27], v[160:163], v[218:221], v[24:27]
	v_mfma_f32_16x16x32_bf16 v[12:15], v[148:151], v[226:229], v[12:15]
	v_mfma_f32_16x16x32_bf16 v[8:11], v[160:163], v[226:229], v[8:11]
	s_setprio 0
	s_setprio 1
	v_mfma_f32_16x16x32_bf16 v[52:55], v[164:167], v[180:183], v[52:55]
	v_mfma_f32_16x16x32_bf16 v[48:51], v[172:175], v[180:183], v[48:51]
	v_mfma_f32_16x16x32_bf16 v[36:39], v[164:167], v[188:191], v[36:39]
	v_mfma_f32_16x16x32_bf16 v[32:35], v[172:175], v[188:191], v[32:35]
	v_mfma_f32_16x16x32_bf16 v[20:23], v[164:167], v[214:217], v[20:23]
	v_mfma_f32_16x16x32_bf16 v[16:19], v[172:175], v[214:217], v[16:19]
	v_mfma_f32_16x16x32_bf16 v[4:7], v[164:167], v[222:225], v[4:7]
	v_mfma_f32_16x16x32_bf16 v[0:3], v[172:175], v[222:225], v[0:3]
	v_mfma_f32_16x16x32_bf16 v[52:55], v[168:171], v[184:187], v[52:55]
	v_mfma_f32_16x16x32_bf16 v[48:51], v[176:179], v[184:187], v[48:51]
	v_mfma_f32_16x16x32_bf16 v[36:39], v[168:171], v[192:195], v[36:39]
	v_mfma_f32_16x16x32_bf16 v[32:35], v[176:179], v[192:195], v[32:35]
	v_mfma_f32_16x16x32_bf16 v[20:23], v[168:171], v[218:221], v[20:23]
	v_mfma_f32_16x16x32_bf16 v[16:19], v[176:179], v[218:221], v[16:19]
	v_mfma_f32_16x16x32_bf16 v[4:7], v[168:171], v[226:229], v[4:7]
	v_mfma_f32_16x16x32_bf16 v[0:3], v[176:179], v[226:229], v[0:3]
	s_setprio 0
	s_barrier
	s_add_i32 s60, 0, 0x18000
	v_add_u32_e32 v159, s60, v141
	s_add_i32 s61, 0, 0x1c000
	ds_read_b128 v[144:147], v159
	ds_read_b128 v[148:151], v159 offset:1024
	ds_read_b128 v[152:155], v159 offset:2048
	ds_read_b128 v[160:163], v159 offset:3072
	v_add_u32_e32 v159, s61, v141
	ds_read_b128 v[164:167], v159
	ds_read_b128 v[168:171], v159 offset:1024
	ds_read_b128 v[172:175], v159 offset:2048
	ds_read_b128 v[176:179], v159 offset:3072
	s_add_u32 s28, s28, s12
	s_addc_u32 s29, s29, s13
	s_mov_b32 m0, s46
	v_lshl_add_u64 v[240:241], s[28:29], 0, v[130:131]
	ds_read_b128 v[180:183], v143 offset:32768
	ds_read_b128 v[184:187], v143 offset:33792
	ds_read_b128 v[188:191], v143 offset:34816
	ds_read_b128 v[192:195], v143 offset:35840
	ds_read_b128 v[214:217], v143 offset:36864
	ds_read_b128 v[218:221], v143 offset:37888
	ds_read_b128 v[222:225], v143 offset:38912
	ds_read_b128 v[226:229], v143 offset:39936
	global_load_lds_dwordx4 v[240:241], off
	v_lshl_add_u64 v[240:241], s[28:29], 0, v[132:133]
	s_mov_b32 m0, s47
	s_nop 0
	global_load_lds_dwordx4 v[240:241], off
	s_waitcnt vmcnt(8)
	s_waitcnt lgkmcnt(0)
	s_barrier
	s_setprio 1
	s_waitcnt lgkmcnt(0)
	v_mfma_f32_16x16x32_bf16 v[122:125], v[144:147], v[180:183], v[122:125]
	v_mfma_f32_16x16x32_bf16 v[126:129], v[152:155], v[180:183], v[126:129]
	v_mfma_f32_16x16x32_bf16 v[110:113], v[144:147], v[188:191], v[110:113]
	v_mfma_f32_16x16x32_bf16 v[106:109], v[152:155], v[188:191], v[106:109]
	v_mfma_f32_16x16x32_bf16 v[94:97], v[144:147], v[214:217], v[94:97]
	v_mfma_f32_16x16x32_bf16 v[88:91], v[152:155], v[214:217], v[88:91]
	v_mfma_f32_16x16x32_bf16 v[76:79], v[144:147], v[222:225], v[76:79]
	v_mfma_f32_16x16x32_bf16 v[72:75], v[152:155], v[222:225], v[72:75]
	v_mfma_f32_16x16x32_bf16 v[122:125], v[148:151], v[184:187], v[122:125]
	v_mfma_f32_16x16x32_bf16 v[126:129], v[160:163], v[184:187], v[126:129]
	v_mfma_f32_16x16x32_bf16 v[110:113], v[148:151], v[192:195], v[110:113]
	v_mfma_f32_16x16x32_bf16 v[106:109], v[160:163], v[192:195], v[106:109]
	v_mfma_f32_16x16x32_bf16 v[94:97], v[148:151], v[218:221], v[94:97]
	v_mfma_f32_16x16x32_bf16 v[88:91], v[160:163], v[218:221], v[88:91]
	v_mfma_f32_16x16x32_bf16 v[76:79], v[148:151], v[226:229], v[76:79]
	v_mfma_f32_16x16x32_bf16 v[72:75], v[160:163], v[226:229], v[72:75]
	s_setprio 0
	s_setprio 1
	v_mfma_f32_16x16x32_bf16 v[118:121], v[164:167], v[180:183], v[118:121]
	v_mfma_f32_16x16x32_bf16 v[114:117], v[172:175], v[180:183], v[114:117]
	v_mfma_f32_16x16x32_bf16 v[102:105], v[164:167], v[188:191], v[102:105]
	v_mfma_f32_16x16x32_bf16 v[98:101], v[172:175], v[188:191], v[98:101]
	v_mfma_f32_16x16x32_bf16 v[84:87], v[164:167], v[214:217], v[84:87]
	v_mfma_f32_16x16x32_bf16 v[80:83], v[172:175], v[214:217], v[80:83]
	v_mfma_f32_16x16x32_bf16 v[68:71], v[164:167], v[222:225], v[68:71]
	v_mfma_f32_16x16x32_bf16 v[64:67], v[172:175], v[222:225], v[64:67]
	v_mfma_f32_16x16x32_bf16 v[118:121], v[168:171], v[184:187], v[118:121]
	v_mfma_f32_16x16x32_bf16 v[114:117], v[176:179], v[184:187], v[114:117]
	v_mfma_f32_16x16x32_bf16 v[102:105], v[168:171], v[192:195], v[102:105]
	v_mfma_f32_16x16x32_bf16 v[98:101], v[176:179], v[192:195], v[98:101]
	v_mfma_f32_16x16x32_bf16 v[84:87], v[168:171], v[218:221], v[84:87]
	v_mfma_f32_16x16x32_bf16 v[80:83], v[176:179], v[218:221], v[80:83]
	v_mfma_f32_16x16x32_bf16 v[68:71], v[168:171], v[226:229], v[68:71]
	v_mfma_f32_16x16x32_bf16 v[64:67], v[176:179], v[226:229], v[64:67]
	s_setprio 0
	s_barrier
	s_add_i32 s28, s60, s39
	v_lshl_add_u64 v[156:157], v[156:157], 0, s[80:81]
	s_mov_b32 m0, s28
	ds_read_b128 v[180:183], v143 offset:49152
	ds_read_b128 v[184:187], v143 offset:50176
	ds_read_b128 v[188:191], v143 offset:51200
	ds_read_b128 v[192:195], v143 offset:52224
	ds_read_b128 v[214:217], v143 offset:53248
	ds_read_b128 v[218:221], v143 offset:54272
	ds_read_b128 v[222:225], v143 offset:55296
	ds_read_b128 v[226:229], v143 offset:56320
	global_load_lds_dwordx4 v[156:157], off
	v_lshl_add_u64 v[156:157], v[230:231], 0, s[80:81]
	s_add_i32 m0, s28, 0x2000
	s_add_i32 s28, s61, s39
	global_load_lds_dwordx4 v[156:157], off
	v_lshl_add_u64 v[156:157], v[232:233], 0, s[80:81]
	s_mov_b32 m0, s28
	s_nop 0
	global_load_lds_dwordx4 v[156:157], off
	v_lshl_add_u64 v[156:157], v[234:235], 0, s[80:81]
	s_add_i32 m0, s28, 0x2000
	s_nop 0
	global_load_lds_dwordx4 v[156:157], off
	v_lshl_add_u64 v[156:157], v[236:237], 0, s[80:81]
	s_mov_b32 m0, s51
	s_nop 0
	global_load_lds_dwordx4 v[156:157], off
	v_lshl_add_u64 v[156:157], v[238:239], 0, s[80:81]
	s_mov_b32 m0, s52
	s_nop 0
	global_load_lds_dwordx4 v[156:157], off
	s_waitcnt vmcnt(8)
	s_waitcnt lgkmcnt(0)
	s_barrier
	s_setprio 1
	s_waitcnt lgkmcnt(0)
	v_mfma_f32_16x16x32_bf16 v[60:63], v[144:147], v[180:183], v[60:63]
	v_mfma_f32_16x16x32_bf16 v[56:59], v[152:155], v[180:183], v[56:59]
	v_mfma_f32_16x16x32_bf16 v[44:47], v[144:147], v[188:191], v[44:47]
	v_mfma_f32_16x16x32_bf16 v[40:43], v[152:155], v[188:191], v[40:43]
	v_mfma_f32_16x16x32_bf16 v[28:31], v[144:147], v[214:217], v[28:31]
	v_mfma_f32_16x16x32_bf16 v[24:27], v[152:155], v[214:217], v[24:27]
	v_mfma_f32_16x16x32_bf16 v[12:15], v[144:147], v[222:225], v[12:15]
	v_mfma_f32_16x16x32_bf16 v[8:11], v[152:155], v[222:225], v[8:11]
	v_mfma_f32_16x16x32_bf16 v[60:63], v[148:151], v[184:187], v[60:63]
	v_mfma_f32_16x16x32_bf16 v[56:59], v[160:163], v[184:187], v[56:59]
	v_mfma_f32_16x16x32_bf16 v[44:47], v[148:151], v[192:195], v[44:47]
	v_mfma_f32_16x16x32_bf16 v[40:43], v[160:163], v[192:195], v[40:43]
	v_mfma_f32_16x16x32_bf16 v[28:31], v[148:151], v[218:221], v[28:31]
	v_mfma_f32_16x16x32_bf16 v[24:27], v[160:163], v[218:221], v[24:27]
	v_mfma_f32_16x16x32_bf16 v[12:15], v[148:151], v[226:229], v[12:15]
	v_mfma_f32_16x16x32_bf16 v[8:11], v[160:163], v[226:229], v[8:11]
	s_setprio 0
	s_setprio 1
	v_mfma_f32_16x16x32_bf16 v[52:55], v[164:167], v[180:183], v[52:55]
	v_mfma_f32_16x16x32_bf16 v[48:51], v[172:175], v[180:183], v[48:51]
	v_mfma_f32_16x16x32_bf16 v[36:39], v[164:167], v[188:191], v[36:39]
	v_mfma_f32_16x16x32_bf16 v[32:35], v[172:175], v[188:191], v[32:35]
	v_mfma_f32_16x16x32_bf16 v[20:23], v[164:167], v[214:217], v[20:23]
	v_mfma_f32_16x16x32_bf16 v[16:19], v[172:175], v[214:217], v[16:19]
	v_mfma_f32_16x16x32_bf16 v[4:7], v[164:167], v[222:225], v[4:7]
	v_mfma_f32_16x16x32_bf16 v[0:3], v[172:175], v[222:225], v[0:3]
	v_mfma_f32_16x16x32_bf16 v[52:55], v[168:171], v[184:187], v[52:55]
	v_mfma_f32_16x16x32_bf16 v[48:51], v[176:179], v[184:187], v[48:51]
	v_mfma_f32_16x16x32_bf16 v[36:39], v[168:171], v[192:195], v[36:39]
	v_mfma_f32_16x16x32_bf16 v[32:35], v[176:179], v[192:195], v[32:35]
	v_mfma_f32_16x16x32_bf16 v[20:23], v[168:171], v[218:221], v[20:23]
	v_mfma_f32_16x16x32_bf16 v[16:19], v[176:179], v[218:221], v[16:19]
	v_mfma_f32_16x16x32_bf16 v[4:7], v[168:171], v[226:229], v[4:7]
	v_mfma_f32_16x16x32_bf16 v[0:3], v[176:179], v[226:229], v[0:3]
	s_setprio 0
	s_add_u32 s26, s26, 0x100
	s_addc_u32 s27, s27, 0
	s_add_u32 s57, s57, 0x100
	s_addc_u32 s58, s58, 0
	s_cmp_ge_i32 s59, s48
	s_mov_b32 s28, s59
	s_cbranch_scc1 .Lrot4_exit
	s_add_i32 s59, s28, 2
	s_add_u32 s60, s26, 0x80
	s_addc_u32 s29, s27, 0
	s_add_i32 s62, 0, 0x10000
	s_cmp_eq_u32 s53, s28
	s_cselect_b32 s29, s7, s29
	s_cselect_b32 s28, s6, s60
	v_add_u32_e32 v156, s62, v141
	s_cselect_b32 s61, s25, s58
	s_cselect_b32 s60, s24, s57
	s_add_i32 s63, 0, 0x14000
	s_barrier
	s_branch .Lrot4_body

.Lrot3_body:
	ds_read_b128 v[146:149], v157
	ds_read_b128 v[150:153], v157 offset:1024
	ds_read_b128 v[160:163], v157 offset:2048
	ds_read_b128 v[164:167], v157 offset:3072
	v_add_u32_e32 v157, s63, v155
	ds_read_b128 v[168:171], v157
	ds_read_b128 v[172:175], v157 offset:1024
	ds_read_b128 v[176:179], v157 offset:2048
	ds_read_b128 v[180:183], v157 offset:3072
	v_lshl_add_u64 v[234:235], s[6:7], 0, v[142:143]
	s_add_i32 m0, s38, 0xc000
	ds_read_b128 v[184:187], v156
	ds_read_b128 v[188:191], v156 offset:1024
	ds_read_b128 v[192:195], v156 offset:2048
	ds_read_b128 v[214:217], v156 offset:3072
	ds_read_b128 v[218:221], v156 offset:4096
	ds_read_b128 v[222:225], v156 offset:5120
	ds_read_b128 v[226:229], v156 offset:6144
	ds_read_b128 v[230:233], v156 offset:7168
	global_load_lds_dwordx4 v[234:235], off
	v_lshl_add_u64 v[234:235], s[6:7], 0, v[144:145]
	s_add_i32 m0, s38, 0xe000
	s_nop 0
	global_load_lds_dwordx4 v[234:235], off
	s_waitcnt vmcnt(8)
	s_waitcnt lgkmcnt(0)
	s_barrier
	s_setprio 1
	s_waitcnt lgkmcnt(0)
	v_mfma_f32_16x16x32_bf16 v[126:129], v[146:149], v[184:187], v[126:129]
	v_mfma_f32_16x16x32_bf16 v[122:125], v[160:163], v[184:187], v[122:125]
	v_mfma_f32_16x16x32_bf16 v[118:121], v[146:149], v[192:195], v[118:121]
	v_mfma_f32_16x16x32_bf16 v[114:117], v[160:163], v[192:195], v[114:117]
	v_mfma_f32_16x16x32_bf16 v[110:113], v[146:149], v[218:221], v[110:113]
	v_mfma_f32_16x16x32_bf16 v[106:109], v[160:163], v[218:221], v[106:109]
	v_mfma_f32_16x16x32_bf16 v[102:105], v[146:149], v[226:229], v[102:105]
	v_mfma_f32_16x16x32_bf16 v[98:101], v[160:163], v[226:229], v[98:101]
	v_mfma_f32_16x16x32_bf16 v[126:129], v[150:153], v[188:191], v[126:129]
	v_mfma_f32_16x16x32_bf16 v[122:125], v[164:167], v[188:191], v[122:125]
	v_mfma_f32_16x16x32_bf16 v[118:121], v[150:153], v[214:217], v[118:121]
	v_mfma_f32_16x16x32_bf16 v[114:117], v[164:167], v[214:217], v[114:117]
	v_mfma_f32_16x16x32_bf16 v[110:113], v[150:153], v[222:225], v[110:113]
	v_mfma_f32_16x16x32_bf16 v[106:109], v[164:167], v[222:225], v[106:109]
	v_mfma_f32_16x16x32_bf16 v[102:105], v[150:153], v[230:233], v[102:105]
	v_mfma_f32_16x16x32_bf16 v[98:101], v[164:167], v[230:233], v[98:101]
	s_setprio 0
	s_setprio 1
	v_mfma_f32_16x16x32_bf16 v[60:63], v[168:171], v[184:187], v[60:63]
	v_mfma_f32_16x16x32_bf16 v[56:59], v[176:179], v[184:187], v[56:59]
	v_mfma_f32_16x16x32_bf16 v[52:55], v[168:171], v[192:195], v[52:55]
	v_mfma_f32_16x16x32_bf16 v[48:51], v[176:179], v[192:195], v[48:51]
	v_mfma_f32_16x16x32_bf16 v[44:47], v[168:171], v[218:221], v[44:47]
	v_mfma_f32_16x16x32_bf16 v[40:43], v[176:179], v[218:221], v[40:43]
	v_mfma_f32_16x16x32_bf16 v[36:39], v[168:171], v[226:229], v[36:39]
	v_mfma_f32_16x16x32_bf16 v[32:35], v[176:179], v[226:229], v[32:35]
	v_mfma_f32_16x16x32_bf16 v[60:63], v[172:175], v[188:191], v[60:63]
	v_mfma_f32_16x16x32_bf16 v[56:59], v[180:183], v[188:191], v[56:59]
	v_mfma_f32_16x16x32_bf16 v[52:55], v[172:175], v[214:217], v[52:55]
	v_mfma_f32_16x16x32_bf16 v[48:51], v[180:183], v[214:217], v[48:51]
	v_mfma_f32_16x16x32_bf16 v[44:47], v[172:175], v[222:225], v[44:47]
	v_mfma_f32_16x16x32_bf16 v[40:43], v[180:183], v[222:225], v[40:43]
	v_mfma_f32_16x16x32_bf16 v[36:39], v[172:175], v[230:233], v[36:39]
	v_mfma_f32_16x16x32_bf16 v[32:35], v[180:183], v[230:233], v[32:35]
	s_setprio 0
	s_barrier
	s_add_i32 s62, s62, s37
	v_lshl_add_u64 v[234:235], s[60:61], 0, v[92:93]
	s_mov_b32 m0, s62
	ds_read_b128 v[184:187], v156 offset:16384
	ds_read_b128 v[188:191], v156 offset:17408
	ds_read_b128 v[192:195], v156 offset:18432
	ds_read_b128 v[214:217], v156 offset:19456
	ds_read_b128 v[218:221], v156 offset:20480
	ds_read_b128 v[222:225], v156 offset:21504
	ds_read_b128 v[226:229], v156 offset:22528
	ds_read_b128 v[230:233], v156 offset:23552
	global_load_lds_dwordx4 v[234:235], off
	s_add_i32 m0, s62, 0x2000
	v_lshl_add_u64 v[236:237], s[60:61], 0, v[134:135]
	s_add_u32 s60, s60, s8
	s_addc_u32 s61, s61, s9
	s_add_i32 s62, s63, s37
	global_load_lds_dwordx4 v[236:237], off
	v_lshl_add_u64 v[238:239], s[60:61], 0, v[92:93]
	s_mov_b32 m0, s62
	v_lshl_add_u64 v[240:241], s[60:61], 0, v[134:135]
	global_load_lds_dwordx4 v[238:239], off
	s_add_i32 m0, s62, 0x2000
	v_lshl_add_u64 v[242:243], s[28:29], 0, v[130:131]
	global_load_lds_dwordx4 v[240:241], off
	s_mov_b32 m0, s38
	v_lshl_add_u64 v[244:245], s[28:29], 0, v[132:133]
	global_load_lds_dwordx4 v[242:243], off
	s_mov_b32 m0, s39
	s_nop 0
	global_load_lds_dwordx4 v[244:245], off
	s_waitcnt vmcnt(8)
	s_waitcnt lgkmcnt(0)
	s_barrier
	s_setprio 1
	s_waitcnt lgkmcnt(0)
	v_mfma_f32_16x16x32_bf16 v[94:97], v[146:149], v[184:187], v[94:97]
	v_mfma_f32_16x16x32_bf16 v[88:91], v[160:163], v[184:187], v[88:91]
	v_mfma_f32_16x16x32_bf16 v[84:87], v[146:149], v[192:195], v[84:87]
	v_mfma_f32_16x16x32_bf16 v[80:83], v[160:163], v[192:195], v[80:83]
	v_mfma_f32_16x16x32_bf16 v[76:79], v[146:149], v[218:221], v[76:79]
	v_mfma_f32_16x16x32_bf16 v[72:75], v[160:163], v[218:221], v[72:75]
	v_mfma_f32_16x16x32_bf16 v[68:71], v[146:149], v[226:229], v[68:71]
	v_mfma_f32_16x16x32_bf16 v[64:67], v[160:163], v[226:229], v[64:67]
	v_mfma_f32_16x16x32_bf16 v[94:97], v[150:153], v[188:191], v[94:97]
	v_mfma_f32_16x16x32_bf16 v[88:91], v[164:167], v[188:191], v[88:91]
	v_mfma_f32_16x16x32_bf16 v[84:87], v[150:153], v[214:217], v[84:87]
	v_mfma_f32_16x16x32_bf16 v[80:83], v[164:167], v[214:217], v[80:83]
	v_mfma_f32_16x16x32_bf16 v[76:79], v[150:153], v[222:225], v[76:79]
	v_mfma_f32_16x16x32_bf16 v[72:75], v[164:167], v[222:225], v[72:75]
	v_mfma_f32_16x16x32_bf16 v[68:71], v[150:153], v[230:233], v[68:71]
	v_mfma_f32_16x16x32_bf16 v[64:67], v[164:167], v[230:233], v[64:67]
	s_setprio 0
	s_setprio 1
	v_mfma_f32_16x16x32_bf16 v[28:31], v[168:171], v[184:187], v[28:31]
	v_mfma_f32_16x16x32_bf16 v[24:27], v[176:179], v[184:187], v[24:27]
	v_mfma_f32_16x16x32_bf16 v[20:23], v[168:171], v[192:195], v[20:23]
	v_mfma_f32_16x16x32_bf16 v[16:19], v[176:179], v[192:195], v[16:19]
	v_mfma_f32_16x16x32_bf16 v[12:15], v[168:171], v[218:221], v[12:15]
	v_mfma_f32_16x16x32_bf16 v[8:11], v[176:179], v[218:221], v[8:11]
	v_mfma_f32_16x16x32_bf16 v[4:7], v[168:171], v[226:229], v[4:7]
	v_mfma_f32_16x16x32_bf16 v[0:3], v[176:179], v[226:229], v[0:3]
	v_mfma_f32_16x16x32_bf16 v[28:31], v[172:175], v[188:191], v[28:31]
	v_mfma_f32_16x16x32_bf16 v[24:27], v[180:183], v[188:191], v[24:27]
	v_mfma_f32_16x16x32_bf16 v[20:23], v[172:175], v[214:217], v[20:23]
	v_mfma_f32_16x16x32_bf16 v[16:19], v[180:183], v[214:217], v[16:19]
	v_mfma_f32_16x16x32_bf16 v[12:15], v[172:175], v[222:225], v[12:15]
	v_mfma_f32_16x16x32_bf16 v[8:11], v[180:183], v[222:225], v[8:11]
	v_mfma_f32_16x16x32_bf16 v[4:7], v[172:175], v[230:233], v[4:7]
	v_mfma_f32_16x16x32_bf16 v[0:3], v[180:183], v[230:233], v[0:3]
	s_setprio 0
	s_barrier
	s_add_i32 s60, 0, 0x18000
	v_add_u32_e32 v157, s60, v155
	s_add_i32 s61, 0, 0x1c000
	ds_read_b128 v[146:149], v157
	ds_read_b128 v[150:153], v157 offset:1024
	ds_read_b128 v[160:163], v157 offset:2048
	ds_read_b128 v[164:167], v157 offset:3072
	v_add_u32_e32 v157, s61, v155
	ds_read_b128 v[168:171], v157
	ds_read_b128 v[172:175], v157 offset:1024
	ds_read_b128 v[176:179], v157 offset:2048
	ds_read_b128 v[180:183], v157 offset:3072
	s_add_u32 s28, s28, s12
	s_addc_u32 s29, s29, s13
	s_mov_b32 m0, s40
	v_lshl_add_u64 v[246:247], s[28:29], 0, v[130:131]
	ds_read_b128 v[184:187], v156 offset:32768
	ds_read_b128 v[188:191], v156 offset:33792
	ds_read_b128 v[192:195], v156 offset:34816
	ds_read_b128 v[214:217], v156 offset:35840
	ds_read_b128 v[218:221], v156 offset:36864
	ds_read_b128 v[222:225], v156 offset:37888
	ds_read_b128 v[226:229], v156 offset:38912
	ds_read_b128 v[230:233], v156 offset:39936
	global_load_lds_dwordx4 v[246:247], off
	v_lshl_add_u64 v[246:247], s[28:29], 0, v[132:133]
	s_mov_b32 m0, s41
	s_nop 0
	global_load_lds_dwordx4 v[246:247], off
	s_waitcnt vmcnt(8)
	s_waitcnt lgkmcnt(0)
	s_barrier
	s_setprio 1
	s_waitcnt lgkmcnt(0)
	v_mfma_f32_16x16x32_bf16 v[126:129], v[146:149], v[184:187], v[126:129]
	v_mfma_f32_16x16x32_bf16 v[122:125], v[160:163], v[184:187], v[122:125]
	v_mfma_f32_16x16x32_bf16 v[118:121], v[146:149], v[192:195], v[118:121]
	v_mfma_f32_16x16x32_bf16 v[114:117], v[160:163], v[192:195], v[114:117]
	v_mfma_f32_16x16x32_bf16 v[110:113], v[146:149], v[218:221], v[110:113]
	v_mfma_f32_16x16x32_bf16 v[106:109], v[160:163], v[218:221], v[106:109]
	v_mfma_f32_16x16x32_bf16 v[102:105], v[146:149], v[226:229], v[102:105]
	v_mfma_f32_16x16x32_bf16 v[98:101], v[160:163], v[226:229], v[98:101]
	v_mfma_f32_16x16x32_bf16 v[126:129], v[150:153], v[188:191], v[126:129]
	v_mfma_f32_16x16x32_bf16 v[122:125], v[164:167], v[188:191], v[122:125]
	v_mfma_f32_16x16x32_bf16 v[118:121], v[150:153], v[214:217], v[118:121]
	v_mfma_f32_16x16x32_bf16 v[114:117], v[164:167], v[214:217], v[114:117]
	v_mfma_f32_16x16x32_bf16 v[110:113], v[150:153], v[222:225], v[110:113]
	v_mfma_f32_16x16x32_bf16 v[106:109], v[164:167], v[222:225], v[106:109]
	v_mfma_f32_16x16x32_bf16 v[102:105], v[150:153], v[230:233], v[102:105]
	v_mfma_f32_16x16x32_bf16 v[98:101], v[164:167], v[230:233], v[98:101]
	s_setprio 0
	s_setprio 1
	v_mfma_f32_16x16x32_bf16 v[60:63], v[168:171], v[184:187], v[60:63]
	v_mfma_f32_16x16x32_bf16 v[56:59], v[176:179], v[184:187], v[56:59]
	v_mfma_f32_16x16x32_bf16 v[52:55], v[168:171], v[192:195], v[52:55]
	v_mfma_f32_16x16x32_bf16 v[48:51], v[176:179], v[192:195], v[48:51]
	v_mfma_f32_16x16x32_bf16 v[44:47], v[168:171], v[218:221], v[44:47]
	v_mfma_f32_16x16x32_bf16 v[40:43], v[176:179], v[218:221], v[40:43]
	v_mfma_f32_16x16x32_bf16 v[36:39], v[168:171], v[226:229], v[36:39]
	v_mfma_f32_16x16x32_bf16 v[32:35], v[176:179], v[226:229], v[32:35]
	v_mfma_f32_16x16x32_bf16 v[60:63], v[172:175], v[188:191], v[60:63]
	v_mfma_f32_16x16x32_bf16 v[56:59], v[180:183], v[188:191], v[56:59]
	v_mfma_f32_16x16x32_bf16 v[52:55], v[172:175], v[214:217], v[52:55]
	v_mfma_f32_16x16x32_bf16 v[48:51], v[180:183], v[214:217], v[48:51]
	v_mfma_f32_16x16x32_bf16 v[44:47], v[172:175], v[222:225], v[44:47]
	v_mfma_f32_16x16x32_bf16 v[40:43], v[180:183], v[222:225], v[40:43]
	v_mfma_f32_16x16x32_bf16 v[36:39], v[172:175], v[230:233], v[36:39]
	v_mfma_f32_16x16x32_bf16 v[32:35], v[180:183], v[230:233], v[32:35]
	s_setprio 0
	s_barrier
	s_add_i32 s28, s60, s37
	v_lshl_add_u64 v[234:235], v[234:235], 0, s[80:81]
	s_mov_b32 m0, s28
	ds_read_b128 v[184:187], v156 offset:49152
	ds_read_b128 v[188:191], v156 offset:50176
	ds_read_b128 v[192:195], v156 offset:51200
	ds_read_b128 v[214:217], v156 offset:52224
	ds_read_b128 v[218:221], v156 offset:53248
	ds_read_b128 v[222:225], v156 offset:54272
	ds_read_b128 v[226:229], v156 offset:55296
	ds_read_b128 v[230:233], v156 offset:56320
	global_load_lds_dwordx4 v[234:235], off
	v_lshl_add_u64 v[234:235], v[236:237], 0, s[80:81]
	s_add_i32 m0, s28, 0x2000
	s_add_i32 s28, s61, s37
	global_load_lds_dwordx4 v[234:235], off
	v_lshl_add_u64 v[234:235], v[238:239], 0, s[80:81]
	s_mov_b32 m0, s28
	s_nop 0
	global_load_lds_dwordx4 v[234:235], off
	v_lshl_add_u64 v[234:235], v[240:241], 0, s[80:81]
	s_add_i32 m0, s28, 0x2000
	s_nop 0
	global_load_lds_dwordx4 v[234:235], off
	v_lshl_add_u64 v[234:235], v[242:243], 0, s[80:81]
	s_mov_b32 m0, s42
	s_nop 0
	global_load_lds_dwordx4 v[234:235], off
	v_lshl_add_u64 v[234:235], v[244:245], 0, s[80:81]
	s_mov_b32 m0, s43
	s_nop 0
	global_load_lds_dwordx4 v[234:235], off
	s_waitcnt vmcnt(8)
	s_waitcnt lgkmcnt(0)
	s_barrier
	s_setprio 1
	s_waitcnt lgkmcnt(0)
	v_mfma_f32_16x16x32_bf16 v[94:97], v[146:149], v[184:187], v[94:97]
	v_mfma_f32_16x16x32_bf16 v[88:91], v[160:163], v[184:187], v[88:91]
	v_mfma_f32_16x16x32_bf16 v[84:87], v[146:149], v[192:195], v[84:87]
	v_mfma_f32_16x16x32_bf16 v[80:83], v[160:163], v[192:195], v[80:83]
	v_mfma_f32_16x16x32_bf16 v[76:79], v[146:149], v[218:221], v[76:79]
	v_mfma_f32_16x16x32_bf16 v[72:75], v[160:163], v[218:221], v[72:75]
	v_mfma_f32_16x16x32_bf16 v[68:71], v[146:149], v[226:229], v[68:71]
	v_mfma_f32_16x16x32_bf16 v[64:67], v[160:163], v[226:229], v[64:67]
	v_mfma_f32_16x16x32_bf16 v[94:97], v[150:153], v[188:191], v[94:97]
	v_mfma_f32_16x16x32_bf16 v[88:91], v[164:167], v[188:191], v[88:91]
	v_mfma_f32_16x16x32_bf16 v[84:87], v[150:153], v[214:217], v[84:87]
	v_mfma_f32_16x16x32_bf16 v[80:83], v[164:167], v[214:217], v[80:83]
	v_mfma_f32_16x16x32_bf16 v[76:79], v[150:153], v[222:225], v[76:79]
	v_mfma_f32_16x16x32_bf16 v[72:75], v[164:167], v[222:225], v[72:75]
	v_mfma_f32_16x16x32_bf16 v[68:71], v[150:153], v[230:233], v[68:71]
	v_mfma_f32_16x16x32_bf16 v[64:67], v[164:167], v[230:233], v[64:67]
	s_setprio 0
	s_setprio 1
	v_mfma_f32_16x16x32_bf16 v[28:31], v[168:171], v[184:187], v[28:31]
	v_mfma_f32_16x16x32_bf16 v[24:27], v[176:179], v[184:187], v[24:27]
	v_mfma_f32_16x16x32_bf16 v[20:23], v[168:171], v[192:195], v[20:23]
	v_mfma_f32_16x16x32_bf16 v[16:19], v[176:179], v[192:195], v[16:19]
	v_mfma_f32_16x16x32_bf16 v[12:15], v[168:171], v[218:221], v[12:15]
	v_mfma_f32_16x16x32_bf16 v[8:11], v[176:179], v[218:221], v[8:11]
	v_mfma_f32_16x16x32_bf16 v[4:7], v[168:171], v[226:229], v[4:7]
	v_mfma_f32_16x16x32_bf16 v[0:3], v[176:179], v[226:229], v[0:3]
	v_mfma_f32_16x16x32_bf16 v[28:31], v[172:175], v[188:191], v[28:31]
	v_mfma_f32_16x16x32_bf16 v[24:27], v[180:183], v[188:191], v[24:27]
	v_mfma_f32_16x16x32_bf16 v[20:23], v[172:175], v[214:217], v[20:23]
	v_mfma_f32_16x16x32_bf16 v[16:19], v[180:183], v[214:217], v[16:19]
	v_mfma_f32_16x16x32_bf16 v[12:15], v[172:175], v[222:225], v[12:15]
	v_mfma_f32_16x16x32_bf16 v[8:11], v[180:183], v[222:225], v[8:11]
	v_mfma_f32_16x16x32_bf16 v[4:7], v[172:175], v[230:233], v[4:7]
	v_mfma_f32_16x16x32_bf16 v[0:3], v[180:183], v[230:233], v[0:3]
	s_setprio 0
	s_add_u32 s6, s6, 0x100
	s_addc_u32 s7, s7, 0
	s_add_u32 s30, s30, 0x100
	s_addc_u32 s31, s31, 0
	s_cmp_ge_i32 s59, s44
	s_mov_b32 s28, s59
	s_cbranch_scc1 .Lrot3_exit
	s_add_i32 s59, s28, 2
	s_add_u32 s60, s6, 0x80
	s_addc_u32 s29, s7, 0
	s_add_i32 s62, 0, 0x10000
	s_cmp_eq_u32 s46, s28
	s_cselect_b32 s29, s25, s29
	s_cselect_b32 s28, s24, s60
	v_add_u32_e32 v157, s62, v155
	s_cselect_b32 s61, s27, s31
	s_cselect_b32 s60, s26, s30
	s_add_i32 s63, 0, 0x14000
	s_barrier
	s_branch .Lrot3_body

.Lrot2_body:
	ds_read_b128 v[146:149], v92
	ds_read_b128 v[152:155], v92 offset:1024
	ds_read_b128 v[160:163], v92 offset:2048
	ds_read_b128 v[164:167], v92 offset:3072
	v_add_u32_e32 v92, s61, v150
	ds_read_b128 v[168:171], v92
	ds_read_b128 v[172:175], v92 offset:1024
	ds_read_b128 v[176:179], v92 offset:2048
	ds_read_b128 v[180:183], v92 offset:3072
	v_lshl_add_u64 v[156:157], s[6:7], 0, v[142:143]
	s_add_i32 m0, s40, 0xc000
	ds_read_b128 v[184:187], v151
	ds_read_b128 v[188:191], v151 offset:1024
	ds_read_b128 v[192:195], v151 offset:2048
	ds_read_b128 v[214:217], v151 offset:3072
	ds_read_b128 v[218:221], v151 offset:4096
	ds_read_b128 v[222:225], v151 offset:5120
	ds_read_b128 v[226:229], v151 offset:6144
	ds_read_b128 v[230:233], v151 offset:7168
	global_load_lds_dwordx4 v[156:157], off
	v_lshl_add_u64 v[156:157], s[6:7], 0, v[144:145]
	s_add_i32 m0, s40, 0xe000
	s_nop 0
	global_load_lds_dwordx4 v[156:157], off
	s_waitcnt vmcnt(8)
	s_waitcnt lgkmcnt(0)
	s_barrier
	s_setprio 1
	s_waitcnt lgkmcnt(0)
	v_mfma_f32_16x16x32_bf16 v[126:129], v[146:149], v[184:187], v[126:129]
	v_mfma_f32_16x16x32_bf16 v[122:125], v[160:163], v[184:187], v[122:125]
	v_mfma_f32_16x16x32_bf16 v[118:121], v[146:149], v[192:195], v[118:121]
	v_mfma_f32_16x16x32_bf16 v[114:117], v[160:163], v[192:195], v[114:117]
	v_mfma_f32_16x16x32_bf16 v[110:113], v[146:149], v[218:221], v[110:113]
	v_mfma_f32_16x16x32_bf16 v[106:109], v[160:163], v[218:221], v[106:109]
	v_mfma_f32_16x16x32_bf16 v[102:105], v[146:149], v[226:229], v[102:105]
	v_mfma_f32_16x16x32_bf16 v[98:101], v[160:163], v[226:229], v[98:101]
	v_mfma_f32_16x16x32_bf16 v[126:129], v[152:155], v[188:191], v[126:129]
	v_mfma_f32_16x16x32_bf16 v[122:125], v[164:167], v[188:191], v[122:125]
	v_mfma_f32_16x16x32_bf16 v[118:121], v[152:155], v[214:217], v[118:121]
	v_mfma_f32_16x16x32_bf16 v[114:117], v[164:167], v[214:217], v[114:117]
	v_mfma_f32_16x16x32_bf16 v[110:113], v[152:155], v[222:225], v[110:113]
	v_mfma_f32_16x16x32_bf16 v[106:109], v[164:167], v[222:225], v[106:109]
	v_mfma_f32_16x16x32_bf16 v[102:105], v[152:155], v[230:233], v[102:105]
	v_mfma_f32_16x16x32_bf16 v[98:101], v[164:167], v[230:233], v[98:101]
	s_setprio 0
	s_setprio 1
	v_mfma_f32_16x16x32_bf16 v[60:63], v[168:171], v[184:187], v[60:63]
	v_mfma_f32_16x16x32_bf16 v[56:59], v[176:179], v[184:187], v[56:59]
	v_mfma_f32_16x16x32_bf16 v[52:55], v[168:171], v[192:195], v[52:55]
	v_mfma_f32_16x16x32_bf16 v[48:51], v[176:179], v[192:195], v[48:51]
	v_mfma_f32_16x16x32_bf16 v[44:47], v[168:171], v[218:221], v[44:47]
	v_mfma_f32_16x16x32_bf16 v[40:43], v[176:179], v[218:221], v[40:43]
	v_mfma_f32_16x16x32_bf16 v[36:39], v[168:171], v[226:229], v[36:39]
	v_mfma_f32_16x16x32_bf16 v[32:35], v[176:179], v[226:229], v[32:35]
	v_mfma_f32_16x16x32_bf16 v[60:63], v[172:175], v[188:191], v[60:63]
	v_mfma_f32_16x16x32_bf16 v[56:59], v[180:183], v[188:191], v[56:59]
	v_mfma_f32_16x16x32_bf16 v[52:55], v[172:175], v[214:217], v[52:55]
	v_mfma_f32_16x16x32_bf16 v[48:51], v[180:183], v[214:217], v[48:51]
	v_mfma_f32_16x16x32_bf16 v[44:47], v[172:175], v[222:225], v[44:47]
	v_mfma_f32_16x16x32_bf16 v[40:43], v[180:183], v[222:225], v[40:43]
	v_mfma_f32_16x16x32_bf16 v[36:39], v[172:175], v[230:233], v[36:39]
	v_mfma_f32_16x16x32_bf16 v[32:35], v[180:183], v[230:233], v[32:35]
	s_setprio 0
	s_barrier
	s_add_i32 s64, s64, s39
	v_lshl_add_u64 v[156:157], s[62:63], 0, v[132:133]
	s_mov_b32 m0, s64
	ds_read_b128 v[184:187], v151 offset:16384
	ds_read_b128 v[188:191], v151 offset:17408
	ds_read_b128 v[192:195], v151 offset:18432
	ds_read_b128 v[214:217], v151 offset:19456
	ds_read_b128 v[218:221], v151 offset:20480
	ds_read_b128 v[222:225], v151 offset:21504
	ds_read_b128 v[226:229], v151 offset:22528
	ds_read_b128 v[230:233], v151 offset:23552
	global_load_lds_dwordx4 v[156:157], off
	s_add_i32 m0, s64, 0x2000
	v_lshl_add_u64 v[234:235], s[62:63], 0, v[136:137]
	s_add_u32 s62, s62, s8
	s_addc_u32 s63, s63, s9
	s_add_i32 s61, s61, s39
	global_load_lds_dwordx4 v[234:235], off
	v_lshl_add_u64 v[236:237], s[62:63], 0, v[132:133]
	s_mov_b32 m0, s61
	v_lshl_add_u64 v[238:239], s[62:63], 0, v[136:137]
	global_load_lds_dwordx4 v[236:237], off
	s_add_i32 m0, s61, 0x2000
	v_lshl_add_u64 v[240:241], s[30:31], 0, v[130:131]
	global_load_lds_dwordx4 v[238:239], off
	s_mov_b32 m0, s40
	v_lshl_add_u64 v[242:243], s[30:31], 0, v[134:135]
	global_load_lds_dwordx4 v[240:241], off
	s_mov_b32 m0, s41
	s_nop 0
	global_load_lds_dwordx4 v[242:243], off
	s_waitcnt vmcnt(8)
	s_waitcnt lgkmcnt(0)
	s_barrier
	s_setprio 1
	s_waitcnt lgkmcnt(0)
	v_mfma_f32_16x16x32_bf16 v[94:97], v[146:149], v[184:187], v[94:97]
	v_mfma_f32_16x16x32_bf16 v[88:91], v[160:163], v[184:187], v[88:91]
	v_mfma_f32_16x16x32_bf16 v[84:87], v[146:149], v[192:195], v[84:87]
	v_mfma_f32_16x16x32_bf16 v[80:83], v[160:163], v[192:195], v[80:83]
	v_mfma_f32_16x16x32_bf16 v[76:79], v[146:149], v[218:221], v[76:79]
	v_mfma_f32_16x16x32_bf16 v[72:75], v[160:163], v[218:221], v[72:75]
	v_mfma_f32_16x16x32_bf16 v[68:71], v[146:149], v[226:229], v[68:71]
	v_mfma_f32_16x16x32_bf16 v[64:67], v[160:163], v[226:229], v[64:67]
	v_mfma_f32_16x16x32_bf16 v[94:97], v[152:155], v[188:191], v[94:97]
	v_mfma_f32_16x16x32_bf16 v[88:91], v[164:167], v[188:191], v[88:91]
	v_mfma_f32_16x16x32_bf16 v[84:87], v[152:155], v[214:217], v[84:87]
	v_mfma_f32_16x16x32_bf16 v[80:83], v[164:167], v[214:217], v[80:83]
	v_mfma_f32_16x16x32_bf16 v[76:79], v[152:155], v[222:225], v[76:79]
	v_mfma_f32_16x16x32_bf16 v[72:75], v[164:167], v[222:225], v[72:75]
	v_mfma_f32_16x16x32_bf16 v[68:71], v[152:155], v[230:233], v[68:71]
	v_mfma_f32_16x16x32_bf16 v[64:67], v[164:167], v[230:233], v[64:67]
	s_setprio 0
	s_setprio 1
	v_mfma_f32_16x16x32_bf16 v[28:31], v[168:171], v[184:187], v[28:31]
	v_mfma_f32_16x16x32_bf16 v[24:27], v[176:179], v[184:187], v[24:27]
	v_mfma_f32_16x16x32_bf16 v[20:23], v[168:171], v[192:195], v[20:23]
	v_mfma_f32_16x16x32_bf16 v[16:19], v[176:179], v[192:195], v[16:19]
	v_mfma_f32_16x16x32_bf16 v[12:15], v[168:171], v[218:221], v[12:15]
	v_mfma_f32_16x16x32_bf16 v[8:11], v[176:179], v[218:221], v[8:11]
	v_mfma_f32_16x16x32_bf16 v[4:7], v[168:171], v[226:229], v[4:7]
	v_mfma_f32_16x16x32_bf16 v[0:3], v[176:179], v[226:229], v[0:3]
	v_mfma_f32_16x16x32_bf16 v[28:31], v[172:175], v[188:191], v[28:31]
	v_mfma_f32_16x16x32_bf16 v[24:27], v[180:183], v[188:191], v[24:27]
	v_mfma_f32_16x16x32_bf16 v[20:23], v[172:175], v[214:217], v[20:23]
	v_mfma_f32_16x16x32_bf16 v[16:19], v[180:183], v[214:217], v[16:19]
	v_mfma_f32_16x16x32_bf16 v[12:15], v[172:175], v[222:225], v[12:15]
	v_mfma_f32_16x16x32_bf16 v[8:11], v[180:183], v[222:225], v[8:11]
	v_mfma_f32_16x16x32_bf16 v[4:7], v[172:175], v[230:233], v[4:7]
	v_mfma_f32_16x16x32_bf16 v[0:3], v[180:183], v[230:233], v[0:3]
	s_setprio 0
	s_barrier
	s_add_i32 s61, 0, 0x18000
	v_add_u32_e32 v92, s61, v150
	s_add_i32 s62, 0, 0x1c000
	ds_read_b128 v[146:149], v92
	ds_read_b128 v[152:155], v92 offset:1024
	ds_read_b128 v[160:163], v92 offset:2048
	ds_read_b128 v[164:167], v92 offset:3072
	v_add_u32_e32 v92, s62, v150
	ds_read_b128 v[168:171], v92
	ds_read_b128 v[172:175], v92 offset:1024
	ds_read_b128 v[176:179], v92 offset:2048
	ds_read_b128 v[180:183], v92 offset:3072
	s_add_u32 s30, s30, s12
	s_addc_u32 s31, s31, s13
	s_mov_b32 m0, s42
	v_lshl_add_u64 v[244:245], s[30:31], 0, v[130:131]
	ds_read_b128 v[184:187], v151 offset:32768
	ds_read_b128 v[188:191], v151 offset:33792
	ds_read_b128 v[192:195], v151 offset:34816
	ds_read_b128 v[214:217], v151 offset:35840
	ds_read_b128 v[218:221], v151 offset:36864
	ds_read_b128 v[222:225], v151 offset:37888
	ds_read_b128 v[226:229], v151 offset:38912
	ds_read_b128 v[230:233], v151 offset:39936
	global_load_lds_dwordx4 v[244:245], off
	v_lshl_add_u64 v[244:245], s[30:31], 0, v[134:135]
	s_mov_b32 m0, s43
	s_nop 0
	global_load_lds_dwordx4 v[244:245], off
	s_waitcnt vmcnt(8)
	s_waitcnt lgkmcnt(0)
	s_barrier
	s_setprio 1
	s_waitcnt lgkmcnt(0)
	v_mfma_f32_16x16x32_bf16 v[126:129], v[146:149], v[184:187], v[126:129]
	v_mfma_f32_16x16x32_bf16 v[122:125], v[160:163], v[184:187], v[122:125]
	v_mfma_f32_16x16x32_bf16 v[118:121], v[146:149], v[192:195], v[118:121]
	v_mfma_f32_16x16x32_bf16 v[114:117], v[160:163], v[192:195], v[114:117]
	v_mfma_f32_16x16x32_bf16 v[110:113], v[146:149], v[218:221], v[110:113]
	v_mfma_f32_16x16x32_bf16 v[106:109], v[160:163], v[218:221], v[106:109]
	v_mfma_f32_16x16x32_bf16 v[102:105], v[146:149], v[226:229], v[102:105]
	v_mfma_f32_16x16x32_bf16 v[98:101], v[160:163], v[226:229], v[98:101]
	v_mfma_f32_16x16x32_bf16 v[126:129], v[152:155], v[188:191], v[126:129]
	v_mfma_f32_16x16x32_bf16 v[122:125], v[164:167], v[188:191], v[122:125]
	v_mfma_f32_16x16x32_bf16 v[118:121], v[152:155], v[214:217], v[118:121]
	v_mfma_f32_16x16x32_bf16 v[114:117], v[164:167], v[214:217], v[114:117]
	v_mfma_f32_16x16x32_bf16 v[110:113], v[152:155], v[222:225], v[110:113]
	v_mfma_f32_16x16x32_bf16 v[106:109], v[164:167], v[222:225], v[106:109]
	v_mfma_f32_16x16x32_bf16 v[102:105], v[152:155], v[230:233], v[102:105]
	v_mfma_f32_16x16x32_bf16 v[98:101], v[164:167], v[230:233], v[98:101]
	s_setprio 0
	s_setprio 1
	v_mfma_f32_16x16x32_bf16 v[60:63], v[168:171], v[184:187], v[60:63]
	v_mfma_f32_16x16x32_bf16 v[56:59], v[176:179], v[184:187], v[56:59]
	v_mfma_f32_16x16x32_bf16 v[52:55], v[168:171], v[192:195], v[52:55]
	v_mfma_f32_16x16x32_bf16 v[48:51], v[176:179], v[192:195], v[48:51]
	v_mfma_f32_16x16x32_bf16 v[44:47], v[168:171], v[218:221], v[44:47]
	v_mfma_f32_16x16x32_bf16 v[40:43], v[176:179], v[218:221], v[40:43]
	v_mfma_f32_16x16x32_bf16 v[36:39], v[168:171], v[226:229], v[36:39]
	v_mfma_f32_16x16x32_bf16 v[32:35], v[176:179], v[226:229], v[32:35]
	v_mfma_f32_16x16x32_bf16 v[60:63], v[172:175], v[188:191], v[60:63]
	v_mfma_f32_16x16x32_bf16 v[56:59], v[180:183], v[188:191], v[56:59]
	v_mfma_f32_16x16x32_bf16 v[52:55], v[172:175], v[214:217], v[52:55]
	v_mfma_f32_16x16x32_bf16 v[48:51], v[180:183], v[214:217], v[48:51]
	v_mfma_f32_16x16x32_bf16 v[44:47], v[172:175], v[222:225], v[44:47]
	v_mfma_f32_16x16x32_bf16 v[40:43], v[180:183], v[222:225], v[40:43]
	v_mfma_f32_16x16x32_bf16 v[36:39], v[172:175], v[230:233], v[36:39]
	v_mfma_f32_16x16x32_bf16 v[32:35], v[180:183], v[230:233], v[32:35]
	s_setprio 0
	s_barrier
	s_add_i32 s30, s61, s39
	v_lshl_add_u64 v[156:157], v[156:157], 0, s[80:81]
	s_mov_b32 m0, s30
	ds_read_b128 v[184:187], v151 offset:49152
	ds_read_b128 v[188:191], v151 offset:50176
	ds_read_b128 v[192:195], v151 offset:51200
	ds_read_b128 v[214:217], v151 offset:52224
	ds_read_b128 v[218:221], v151 offset:53248
	ds_read_b128 v[222:225], v151 offset:54272
	ds_read_b128 v[226:229], v151 offset:55296
	ds_read_b128 v[230:233], v151 offset:56320
	global_load_lds_dwordx4 v[156:157], off
	v_lshl_add_u64 v[156:157], v[234:235], 0, s[80:81]
	s_add_i32 m0, s30, 0x2000
	s_add_i32 s30, s62, s39
	global_load_lds_dwordx4 v[156:157], off
	v_lshl_add_u64 v[156:157], v[236:237], 0, s[80:81]
	s_mov_b32 m0, s30
	s_nop 0
	global_load_lds_dwordx4 v[156:157], off
	v_lshl_add_u64 v[156:157], v[238:239], 0, s[80:81]
	s_add_i32 m0, s30, 0x2000
	s_nop 0
	global_load_lds_dwordx4 v[156:157], off
	v_lshl_add_u64 v[156:157], v[240:241], 0, s[80:81]
	s_mov_b32 m0, s45
	s_nop 0
	global_load_lds_dwordx4 v[156:157], off
	v_lshl_add_u64 v[156:157], v[242:243], 0, s[80:81]
	s_mov_b32 m0, s46
	s_nop 0
	global_load_lds_dwordx4 v[156:157], off
	s_waitcnt vmcnt(8)
	s_waitcnt lgkmcnt(0)
	s_barrier
	s_setprio 1
	s_waitcnt lgkmcnt(0)
	v_mfma_f32_16x16x32_bf16 v[94:97], v[146:149], v[184:187], v[94:97]
	v_mfma_f32_16x16x32_bf16 v[88:91], v[160:163], v[184:187], v[88:91]
	v_mfma_f32_16x16x32_bf16 v[84:87], v[146:149], v[192:195], v[84:87]
	v_mfma_f32_16x16x32_bf16 v[80:83], v[160:163], v[192:195], v[80:83]
	v_mfma_f32_16x16x32_bf16 v[76:79], v[146:149], v[218:221], v[76:79]
	v_mfma_f32_16x16x32_bf16 v[72:75], v[160:163], v[218:221], v[72:75]
	v_mfma_f32_16x16x32_bf16 v[68:71], v[146:149], v[226:229], v[68:71]
	v_mfma_f32_16x16x32_bf16 v[64:67], v[160:163], v[226:229], v[64:67]
	v_mfma_f32_16x16x32_bf16 v[94:97], v[152:155], v[188:191], v[94:97]
	v_mfma_f32_16x16x32_bf16 v[88:91], v[164:167], v[188:191], v[88:91]
	v_mfma_f32_16x16x32_bf16 v[84:87], v[152:155], v[214:217], v[84:87]
	v_mfma_f32_16x16x32_bf16 v[80:83], v[164:167], v[214:217], v[80:83]
	v_mfma_f32_16x16x32_bf16 v[76:79], v[152:155], v[222:225], v[76:79]
	v_mfma_f32_16x16x32_bf16 v[72:75], v[164:167], v[222:225], v[72:75]
	v_mfma_f32_16x16x32_bf16 v[68:71], v[152:155], v[230:233], v[68:71]
	v_mfma_f32_16x16x32_bf16 v[64:67], v[164:167], v[230:233], v[64:67]
	s_setprio 0
	s_setprio 1
	v_mfma_f32_16x16x32_bf16 v[28:31], v[168:171], v[184:187], v[28:31]
	v_mfma_f32_16x16x32_bf16 v[24:27], v[176:179], v[184:187], v[24:27]
	v_mfma_f32_16x16x32_bf16 v[20:23], v[168:171], v[192:195], v[20:23]
	v_mfma_f32_16x16x32_bf16 v[16:19], v[176:179], v[192:195], v[16:19]
	v_mfma_f32_16x16x32_bf16 v[12:15], v[168:171], v[218:221], v[12:15]
	v_mfma_f32_16x16x32_bf16 v[8:11], v[176:179], v[218:221], v[8:11]
	v_mfma_f32_16x16x32_bf16 v[4:7], v[168:171], v[226:229], v[4:7]
	v_mfma_f32_16x16x32_bf16 v[0:3], v[176:179], v[226:229], v[0:3]
	v_mfma_f32_16x16x32_bf16 v[28:31], v[172:175], v[188:191], v[28:31]
	v_mfma_f32_16x16x32_bf16 v[24:27], v[180:183], v[188:191], v[24:27]
	v_mfma_f32_16x16x32_bf16 v[20:23], v[172:175], v[214:217], v[20:23]
	v_mfma_f32_16x16x32_bf16 v[16:19], v[180:183], v[214:217], v[16:19]
	v_mfma_f32_16x16x32_bf16 v[12:15], v[172:175], v[222:225], v[12:15]
	v_mfma_f32_16x16x32_bf16 v[8:11], v[180:183], v[222:225], v[8:11]
	v_mfma_f32_16x16x32_bf16 v[4:7], v[172:175], v[230:233], v[4:7]
	v_mfma_f32_16x16x32_bf16 v[0:3], v[180:183], v[230:233], v[0:3]
	s_setprio 0
	s_add_u32 s6, s6, 0x100
	s_addc_u32 s7, s7, 0
	s_add_u32 s34, s34, 0x100
	s_addc_u32 s35, s35, 0
	s_cmp_ge_i32 s60, s44
	s_mov_b32 s30, s60
	s_cbranch_scc1 .Lrot2_exit
	s_add_i32 s60, s30, 2
	s_add_u32 s61, s6, 0x80
	s_addc_u32 s31, s7, 0
	s_add_i32 s64, 0, 0x10000
	s_cmp_eq_u32 s47, s30
	s_cselect_b32 s31, s27, s31
	s_cselect_b32 s30, s26, s61
	v_add_u32_e32 v92, s64, v150
	s_cselect_b32 s63, s29, s35
	s_cselect_b32 s62, s28, s34
	s_add_i32 s61, 0, 0x14000
	s_barrier
	s_branch .Lrot2_body
